# K-loop first iteration peeled with C=0 (no accumulator zeroing) for P_in and P_out GEMMs; attention next-tile LDS writes issued under the exp section
# speedup vs baseline: 1.0038x; 1.0038x over previous
; #define PG8_STAGE(bufoff, gbase, voff) do { _Pragma("unroll") for (int _i = 0; _i < 2; ++_i) \
;         __builtin_amdgcn_global_load_lds((const unsigned*)((const char*)(gbase) + (voff)[_i]), (LAS unsigned*)(lds + (bufoff) + ldsw + _i * 8192), 16, 0, 0); } while (0)
; #define PG8_LDA(dst, b, h) do { _Pragma("unroll") for (int m = 0; m < 4; ++m) _Pragma("unroll") for (int k = 0; k < 2; ++k) dst[m][k] = *(const LAS bf16x8*)(lds + PG8_SA(b, h) + aoff + m * 2048 + k * 1024); } while (0)
; #define PG8_BAR __builtin_amdgcn_s_barrier()
; template <class Epi, class Sched, bool ALIGN_EPI, bool I8 = false>
; __device__ __forceinline__ void gemm_phase(LAS unsigned char* lds, const Gemm g, const Sched& S, const Epi& E) {
;     ...
;         const bool has_next = S.next(ui + 1, nxt);
;         const char* nA = has_next ? (const char*)g.A + (size_t)nxt.z * g.zA + (size_t)nxt.pm * tstep : cA;
;         const char* nB = has_next ? (const char*)g.Bt + (size_t)nxt.z * g.zB + (size_t)nxt.pn * tstep : cB;
;         for (int t = 0; t < nt; t += 2) {
;             const bool last = (t == nt - 2);
;             const char* a1 = cA + (size_t)(t + 1) * kstep;
;             const char* a2 = last ? nA : cA + (size_t)(t + 2) * kstep; const char* b2 = last ? nB : cB + (size_t)(t + 2) * kstep;
;             const char* a3 = a2 + kstep; const char* b3 = b2 + kstep;
;             PG8_LDB(B0, 0, 0); PG8_LDB(B1, 0, 1); PG8_SCHED; PG8_LDA(At, 0, 0); PG8_STAGE(PG8_SA(1, 1), a1 + hstep, voffA);
;             PG8_WAIT_V(8); PG8_WAIT_L(0); PG8_BAR; PG8_MMA(0, 0, At, B0); PG8_MMA(0, 1, At, B1); PG8_BAR; PG8_SCHED;
;             PG8_LDA(At, 0, 1); PG8_STAGE(PG8_SB(0, 0), b2, voffB); PG8_STAGE(PG8_SB(0, 1), b2 + hstep, voffB); PG8_STAGE(PG8_SA(0, 0), a2, voffA);
;             PG8_WAIT_V(8); PG8_WAIT_L(0); PG8_BAR; PG8_MMA(1, 0, At, B0); PG8_MMA(1, 1, At, B1); PG8_BAR; PG8_SCHED;
;             PG8_LDB(B0, 1, 0); PG8_LDB(B1, 1, 1); PG8_SCHED; PG8_LDA(At, 1, 0); PG8_STAGE(PG8_SA(0, 1), a2 + hstep, voffA);
;             PG8_WAIT_V(8); PG8_WAIT_L(0); PG8_BAR; PG8_MMA(0, 0, At, B0); PG8_MMA(0, 1, At, B1); PG8_BAR; PG8_SCHED;
;             PG8_LDA(At, 1, 1); PG8_STAGE(PG8_SB(1, 0), b3, voffB); PG8_STAGE(PG8_SB(1, 1), b3 + hstep, voffB); PG8_STAGE(PG8_SA(1, 0), a3, voffA);
;             PG8_WAIT_V(8); PG8_WAIT_L(0); PG8_BAR; PG8_MMA(1, 0, At, B0); PG8_MMA(1, 1, At, B1); PG8_BAR; PG8_SCHED;
.LBB0_118:
	s_ashr_i32 s35, s34, 31
	s_lshl_b64 s[36:37], s[34:35], 20
	s_add_u32 s36, s49, s36
	s_addc_u32 s37, s50, s37
	s_and_b64 s[38:39], s[2:3], exec
	s_cselect_b32 s35, s37, s43
	s_cselect_b32 s41, s36, s42
	s_ashr_i32 s31, s30, 31
	s_lshl_b64 s[38:39], s[30:31], 20
	s_add_u32 s38, s51, s38
	s_addc_u32 s39, s52, s39
	s_and_b64 s[46:47], s[2:3], exec
	s_cselect_b32 s31, s39, s45
	s_cselect_b32 s84, s38, s44
	s_add_u32 s42, s42, 0x80080
	s_addc_u32 s43, s43, 0
	s_add_u32 s86, s44, 0x100
	s_addc_u32 s87, s45, 0
	s_mov_b32 s88, -2
	ds_read_b128 v[146:149], v168
	ds_read_b128 v[172:175], v168 offset:1024
	ds_read_b128 v[176:179], v168 offset:2048
	ds_read_b128 v[180:183], v168 offset:3072
	ds_read_b128 v[184:187], v169
	ds_read_b128 v[188:191], v169 offset:1024
	ds_read_b128 v[192:195], v169 offset:2048
	ds_read_b128 v[196:199], v169 offset:3072
	s_add_u32 s4, s42, 0xfff80080
	s_addc_u32 s5, s43, -1
	s_cmp_eq_u32 s88, 28
	s_cselect_b32 s47, s35, s5
	s_cselect_b32 s46, s41, s4
	s_cselect_b32 s45, s31, s87
	s_cselect_b32 s44, s84, s86
	v_lshl_add_u64 v[150:151], s[42:43], 0, v[138:139]
	s_add_i32 m0, s54, 0xc000
	ds_read_b128 v[200:203], v170
	ds_read_b128 v[204:207], v170 offset:1024
	ds_read_b128 v[208:211], v170 offset:2048
	ds_read_b128 v[212:215], v170 offset:3072
	ds_read_b128 v[218:221], v170 offset:4096
	ds_read_b128 v[222:225], v170 offset:5120
	ds_read_b128 v[226:229], v170 offset:6144
	ds_read_b128 v[230:233], v170 offset:7168
	global_load_lds_dwordx4 v[150:151], off
	v_lshl_add_u64 v[150:151], s[42:43], 0, v[140:141]
	s_add_i32 m0, s54, 0xe000
	s_nop 0
	global_load_lds_dwordx4 v[150:151], off
	s_waitcnt vmcnt(8)
	s_waitcnt lgkmcnt(0)
	s_barrier
	s_setprio 1
	s_waitcnt lgkmcnt(0)
	v_mfma_f32_16x16x32_bf16 v[124:127], v[146:149], v[200:203], 0
	v_mfma_f32_16x16x32_bf16 v[120:123], v[176:179], v[200:203], 0
	v_mfma_f32_16x16x32_bf16 v[108:111], v[146:149], v[208:211], 0
	v_mfma_f32_16x16x32_bf16 v[104:107], v[176:179], v[208:211], 0
	v_mfma_f32_16x16x32_bf16 v[92:95], v[146:149], v[218:221], 0
	v_mfma_f32_16x16x32_bf16 v[88:91], v[176:179], v[218:221], 0
	v_mfma_f32_16x16x32_bf16 v[76:79], v[146:149], v[226:229], 0
	v_mfma_f32_16x16x32_bf16 v[72:75], v[176:179], v[226:229], 0
	v_mfma_f32_16x16x32_bf16 v[124:127], v[172:175], v[204:207], v[124:127]
	v_mfma_f32_16x16x32_bf16 v[120:123], v[180:183], v[204:207], v[120:123]
	v_mfma_f32_16x16x32_bf16 v[108:111], v[172:175], v[212:215], v[108:111]
	v_mfma_f32_16x16x32_bf16 v[104:107], v[180:183], v[212:215], v[104:107]
	v_mfma_f32_16x16x32_bf16 v[92:95], v[172:175], v[222:225], v[92:95]
	v_mfma_f32_16x16x32_bf16 v[88:91], v[180:183], v[222:225], v[88:91]
	v_mfma_f32_16x16x32_bf16 v[76:79], v[172:175], v[230:233], v[76:79]
	v_mfma_f32_16x16x32_bf16 v[72:75], v[180:183], v[230:233], v[72:75]
	s_setprio 0
	s_setprio 1
	v_mfma_f32_16x16x32_bf16 v[116:119], v[184:187], v[200:203], 0
	v_mfma_f32_16x16x32_bf16 v[112:115], v[192:195], v[200:203], 0
	v_mfma_f32_16x16x32_bf16 v[100:103], v[184:187], v[208:211], 0
	v_mfma_f32_16x16x32_bf16 v[96:99], v[192:195], v[208:211], 0
	v_mfma_f32_16x16x32_bf16 v[84:87], v[184:187], v[218:221], 0
	v_mfma_f32_16x16x32_bf16 v[80:83], v[192:195], v[218:221], 0
	v_mfma_f32_16x16x32_bf16 v[68:71], v[184:187], v[226:229], 0
	v_mfma_f32_16x16x32_bf16 v[64:67], v[192:195], v[226:229], 0
	v_mfma_f32_16x16x32_bf16 v[116:119], v[188:191], v[204:207], v[116:119]
	v_mfma_f32_16x16x32_bf16 v[112:115], v[196:199], v[204:207], v[112:115]
	v_mfma_f32_16x16x32_bf16 v[100:103], v[188:191], v[212:215], v[100:103]
	v_mfma_f32_16x16x32_bf16 v[96:99], v[196:199], v[212:215], v[96:99]
	v_mfma_f32_16x16x32_bf16 v[84:87], v[188:191], v[222:225], v[84:87]
	v_mfma_f32_16x16x32_bf16 v[80:83], v[196:199], v[222:225], v[80:83]
	v_mfma_f32_16x16x32_bf16 v[68:71], v[188:191], v[230:233], v[68:71]
	v_mfma_f32_16x16x32_bf16 v[64:67], v[196:199], v[230:233], v[64:67]
	s_setprio 0
	s_barrier
	s_add_i32 s4, s65, s53
	v_lshl_add_u64 v[150:151], s[44:45], 0, v[130:131]
	s_mov_b32 m0, s4
	ds_read_b128 v[200:203], v170 offset:16384
	ds_read_b128 v[204:207], v170 offset:17408
	ds_read_b128 v[208:211], v170 offset:18432
	ds_read_b128 v[212:215], v170 offset:19456
	ds_read_b128 v[218:221], v170 offset:20480
	ds_read_b128 v[222:225], v170 offset:21504
	ds_read_b128 v[226:229], v170 offset:22528
	ds_read_b128 v[230:233], v170 offset:23552
	global_load_lds_dwordx4 v[150:151], off
	s_add_i32 m0, s4, 0x2000
	s_add_u32 s90, s44, 0x80000
	v_lshl_add_u64 v[234:235], s[44:45], 0, v[134:135]
	s_addc_u32 s91, s45, 0
	s_add_i32 s4, s66, s53
	global_load_lds_dwordx4 v[234:235], off
	v_lshl_add_u64 v[236:237], s[90:91], 0, v[130:131]
	s_mov_b32 m0, s4
	v_lshl_add_u64 v[238:239], s[46:47], 0, v[132:133]
	global_load_lds_dwordx4 v[236:237], off
	v_lshl_add_u64 v[236:237], s[90:91], 0, v[134:135]
	s_add_i32 m0, s4, 0x2000
	s_nop 0
	global_load_lds_dwordx4 v[236:237], off
	v_lshl_add_u64 v[236:237], s[46:47], 0, v[128:129]
	s_mov_b32 m0, s54
	s_nop 0
	global_load_lds_dwordx4 v[236:237], off
	s_mov_b32 m0, s55
	s_nop 0
	global_load_lds_dwordx4 v[238:239], off
	s_waitcnt vmcnt(8)
	s_waitcnt lgkmcnt(0)
	s_barrier
; #define PG8_STAGE(bufoff, gbase, voff) do { _Pragma("unroll") for (int _i = 0; _i < 2; ++_i) \
;         __builtin_amdgcn_global_load_lds((const unsigned*)((const char*)(gbase) + (voff)[_i]), (LAS unsigned*)(lds + (bufoff) + ldsw + _i * 8192), 16, 0, 0); } while (0)
; #define PG8_LDA(dst, b, h) do { _Pragma("unroll") for (int m = 0; m < 4; ++m) _Pragma("unroll") for (int k = 0; k < 2; ++k) dst[m][k] = *(const LAS bf16x8*)(lds + PG8_SA(b, h) + aoff + m * 2048 + k * 1024); } while (0)
; #define PG8_LDB(dst, b, h) do { _Pragma("unroll") for (int n = 0; n < 2; ++n) _Pragma("unroll") for (int k = 0; k < 2; ++k) dst[n][k] = *(const LAS bf16x8*)(lds + PG8_SB(b, h) + boff + n * 2048 + k * 1024); } while (0)
; #define PG8_WAIT_V(n) asm volatile("s_waitcnt vmcnt(" #n ")" ::: "memory")
; #define PG8_WAIT_L(n) asm volatile("s_waitcnt lgkmcnt(" #n ")" ::: "memory")
; #define PG8_BAR __builtin_amdgcn_s_barrier()
; #define PG8_SCHED __builtin_amdgcn_sched_barrier(0)
; template <class Epi, class Sched, bool ALIGN_EPI, bool I8 = false>
; __device__ __forceinline__ void gemm_phase(LAS unsigned char* lds, const Gemm g, const Sched& S, const Epi& E) {
;     ...
;             PG8_WAIT_V(8); PG8_WAIT_L(0); PG8_BAR; PG8_MMA(1, 0, At, B0); PG8_MMA(1, 1, At, B1); PG8_BAR; PG8_SCHED;
;             PG8_LDB(B0, 1, 0); PG8_LDB(B1, 1, 1); PG8_SCHED; PG8_LDA(At, 1, 0); PG8_STAGE(PG8_SA(0, 1), a2 + hstep, voffA);
;             PG8_WAIT_V(8); PG8_WAIT_L(0); PG8_BAR; PG8_MMA(0, 0, At, B0); PG8_MMA(0, 1, At, B1); PG8_BAR; PG8_SCHED;
	s_setprio 1
	s_waitcnt lgkmcnt(0)
	v_mfma_f32_16x16x32_bf16 v[60:63], v[146:149], v[200:203], 0
	v_mfma_f32_16x16x32_bf16 v[56:59], v[176:179], v[200:203], 0
	v_mfma_f32_16x16x32_bf16 v[44:47], v[146:149], v[208:211], 0
	v_mfma_f32_16x16x32_bf16 v[40:43], v[176:179], v[208:211], 0
	v_mfma_f32_16x16x32_bf16 v[28:31], v[146:149], v[218:221], 0
	v_mfma_f32_16x16x32_bf16 v[24:27], v[176:179], v[218:221], 0
	v_mfma_f32_16x16x32_bf16 v[12:15], v[146:149], v[226:229], 0
	v_mfma_f32_16x16x32_bf16 v[8:11], v[176:179], v[226:229], 0
	v_mfma_f32_16x16x32_bf16 v[60:63], v[172:175], v[204:207], v[60:63]
	v_mfma_f32_16x16x32_bf16 v[56:59], v[180:183], v[204:207], v[56:59]
	v_mfma_f32_16x16x32_bf16 v[44:47], v[172:175], v[212:215], v[44:47]
	v_mfma_f32_16x16x32_bf16 v[40:43], v[180:183], v[212:215], v[40:43]
	v_mfma_f32_16x16x32_bf16 v[28:31], v[172:175], v[222:225], v[28:31]
	v_mfma_f32_16x16x32_bf16 v[24:27], v[180:183], v[222:225], v[24:27]
	v_mfma_f32_16x16x32_bf16 v[12:15], v[172:175], v[230:233], v[12:15]
	v_mfma_f32_16x16x32_bf16 v[8:11], v[180:183], v[230:233], v[8:11]
	s_setprio 0
	s_setprio 1
	v_mfma_f32_16x16x32_bf16 v[52:55], v[184:187], v[200:203], 0
	v_mfma_f32_16x16x32_bf16 v[48:51], v[192:195], v[200:203], 0
	v_mfma_f32_16x16x32_bf16 v[36:39], v[184:187], v[208:211], 0
	v_mfma_f32_16x16x32_bf16 v[32:35], v[192:195], v[208:211], 0
	v_mfma_f32_16x16x32_bf16 v[20:23], v[184:187], v[218:221], 0
	v_mfma_f32_16x16x32_bf16 v[16:19], v[192:195], v[218:221], 0
	v_mfma_f32_16x16x32_bf16 v[4:7], v[184:187], v[226:229], 0
	v_mfma_f32_16x16x32_bf16 v[0:3], v[192:195], v[226:229], 0
	v_mfma_f32_16x16x32_bf16 v[52:55], v[188:191], v[204:207], v[52:55]
	v_mfma_f32_16x16x32_bf16 v[48:51], v[196:199], v[204:207], v[48:51]
	v_mfma_f32_16x16x32_bf16 v[36:39], v[188:191], v[212:215], v[36:39]
	v_mfma_f32_16x16x32_bf16 v[32:35], v[196:199], v[212:215], v[32:35]
	v_mfma_f32_16x16x32_bf16 v[20:23], v[188:191], v[222:225], v[20:23]
	v_mfma_f32_16x16x32_bf16 v[16:19], v[196:199], v[222:225], v[16:19]
	v_mfma_f32_16x16x32_bf16 v[4:7], v[188:191], v[230:233], v[4:7]
	v_mfma_f32_16x16x32_bf16 v[0:3], v[196:199], v[230:233], v[0:3]
	s_setprio 0
	s_barrier
	s_add_i32 s4, 0, 0x18000
	v_add_u32_e32 v136, s4, v166
	s_add_i32 s5, 0, 0x1c000
	ds_read_b128 v[146:149], v136
	ds_read_b128 v[172:175], v136 offset:1024
	ds_read_b128 v[176:179], v136 offset:2048
	ds_read_b128 v[180:183], v136 offset:3072
	v_add_u32_e32 v136, s5, v166
	ds_read_b128 v[184:187], v136
	ds_read_b128 v[188:191], v136 offset:1024
	ds_read_b128 v[192:195], v136 offset:2048
	ds_read_b128 v[196:199], v136 offset:3072
	s_add_u32 s46, s46, 0x80000
	s_addc_u32 s47, s47, 0
	s_mov_b32 m0, s56
	v_lshl_add_u64 v[240:241], s[46:47], 0, v[128:129]
	ds_read_b128 v[200:203], v170 offset:32768
	ds_read_b128 v[204:207], v170 offset:33792
	ds_read_b128 v[208:211], v170 offset:34816
	ds_read_b128 v[212:215], v170 offset:35840
	ds_read_b128 v[218:221], v170 offset:36864
	ds_read_b128 v[222:225], v170 offset:37888
	ds_read_b128 v[226:229], v170 offset:38912
	ds_read_b128 v[230:233], v170 offset:39936
	global_load_lds_dwordx4 v[240:241], off
	v_lshl_add_u64 v[240:241], s[46:47], 0, v[132:133]
	s_mov_b32 m0, s57
	s_nop 0
	global_load_lds_dwordx4 v[240:241], off
	s_waitcnt vmcnt(8)
	s_waitcnt lgkmcnt(0)
	s_barrier
	s_setprio 1
	s_waitcnt lgkmcnt(0)
	v_mfma_f32_16x16x32_bf16 v[124:127], v[146:149], v[200:203], v[124:127]
	v_mfma_f32_16x16x32_bf16 v[120:123], v[176:179], v[200:203], v[120:123]
	v_mfma_f32_16x16x32_bf16 v[108:111], v[146:149], v[208:211], v[108:111]
	v_mfma_f32_16x16x32_bf16 v[104:107], v[176:179], v[208:211], v[104:107]
	v_mfma_f32_16x16x32_bf16 v[92:95], v[146:149], v[218:221], v[92:95]
	v_mfma_f32_16x16x32_bf16 v[88:91], v[176:179], v[218:221], v[88:91]
	v_mfma_f32_16x16x32_bf16 v[76:79], v[146:149], v[226:229], v[76:79]
	v_mfma_f32_16x16x32_bf16 v[72:75], v[176:179], v[226:229], v[72:75]
	v_mfma_f32_16x16x32_bf16 v[124:127], v[172:175], v[204:207], v[124:127]
	v_mfma_f32_16x16x32_bf16 v[120:123], v[180:183], v[204:207], v[120:123]
	v_mfma_f32_16x16x32_bf16 v[108:111], v[172:175], v[212:215], v[108:111]
	v_mfma_f32_16x16x32_bf16 v[104:107], v[180:183], v[212:215], v[104:107]
	v_mfma_f32_16x16x32_bf16 v[92:95], v[172:175], v[222:225], v[92:95]
	v_mfma_f32_16x16x32_bf16 v[88:91], v[180:183], v[222:225], v[88:91]
	v_mfma_f32_16x16x32_bf16 v[76:79], v[172:175], v[230:233], v[76:79]
	v_mfma_f32_16x16x32_bf16 v[72:75], v[180:183], v[230:233], v[72:75]
	s_setprio 0
	s_setprio 1
	v_mfma_f32_16x16x32_bf16 v[116:119], v[184:187], v[200:203], v[116:119]
	v_mfma_f32_16x16x32_bf16 v[112:115], v[192:195], v[200:203], v[112:115]
	v_mfma_f32_16x16x32_bf16 v[100:103], v[184:187], v[208:211], v[100:103]
	v_mfma_f32_16x16x32_bf16 v[96:99], v[192:195], v[208:211], v[96:99]
	v_mfma_f32_16x16x32_bf16 v[84:87], v[184:187], v[218:221], v[84:87]
	v_mfma_f32_16x16x32_bf16 v[80:83], v[192:195], v[218:221], v[80:83]
	v_mfma_f32_16x16x32_bf16 v[68:71], v[184:187], v[226:229], v[68:71]
	v_mfma_f32_16x16x32_bf16 v[64:67], v[192:195], v[226:229], v[64:67]
	v_mfma_f32_16x16x32_bf16 v[116:119], v[188:191], v[204:207], v[116:119]
	v_mfma_f32_16x16x32_bf16 v[112:115], v[196:199], v[204:207], v[112:115]
	v_mfma_f32_16x16x32_bf16 v[100:103], v[188:191], v[212:215], v[100:103]
	v_mfma_f32_16x16x32_bf16 v[96:99], v[196:199], v[212:215], v[96:99]
	v_mfma_f32_16x16x32_bf16 v[84:87], v[188:191], v[222:225], v[84:87]
	v_mfma_f32_16x16x32_bf16 v[80:83], v[196:199], v[222:225], v[80:83]
	v_mfma_f32_16x16x32_bf16 v[68:71], v[188:191], v[230:233], v[68:71]
	v_mfma_f32_16x16x32_bf16 v[64:67], v[196:199], v[230:233], v[64:67]
	s_setprio 0
	s_barrier
; #define PG8_STAGE(bufoff, gbase, voff) do { _Pragma("unroll") for (int _i = 0; _i < 2; ++_i) \
;         __builtin_amdgcn_global_load_lds((const unsigned*)((const char*)(gbase) + (voff)[_i]), (LAS unsigned*)(lds + (bufoff) + ldsw + _i * 8192), 16, 0, 0); } while (0)
; #define PG8_LDA(dst, b, h) do { _Pragma("unroll") for (int m = 0; m < 4; ++m) _Pragma("unroll") for (int k = 0; k < 2; ++k) dst[m][k] = *(const LAS bf16x8*)(lds + PG8_SA(b, h) + aoff + m * 2048 + k * 1024); } while (0)
; #define PG8_WAIT_V(n) asm volatile("s_waitcnt vmcnt(" #n ")" ::: "memory")
; #define PG8_WAIT_L(n) asm volatile("s_waitcnt lgkmcnt(" #n ")" ::: "memory")
; #define PG8_BAR __builtin_amdgcn_s_barrier()
; #define PG8_SCHED __builtin_amdgcn_sched_barrier(0)
; template <class Epi, class Sched, bool ALIGN_EPI, bool I8 = false>
; __device__ __forceinline__ void gemm_phase(LAS unsigned char* lds, const Gemm g, const Sched& S, const Epi& E) {
;     ...
;             PG8_LDA(At, 1, 1); PG8_STAGE(PG8_SB(1, 0), b3, voffB); PG8_STAGE(PG8_SB(1, 1), b3 + hstep, voffB); PG8_STAGE(PG8_SA(1, 0), a3, voffA);
;             PG8_WAIT_V(8); PG8_WAIT_L(0); PG8_BAR; PG8_MMA(1, 0, At, B0); PG8_MMA(1, 1, At, B1); PG8_BAR; PG8_SCHED;
;         }
	s_add_i32 s4, s4, s53
	v_lshl_add_u64 v[150:151], v[150:151], 0, s[12:13]
	s_mov_b32 m0, s4
	ds_read_b128 v[200:203], v170 offset:49152
	ds_read_b128 v[204:207], v170 offset:50176
	ds_read_b128 v[208:211], v170 offset:51200
	ds_read_b128 v[212:215], v170 offset:52224
	ds_read_b128 v[218:221], v170 offset:53248
	ds_read_b128 v[222:225], v170 offset:54272
	ds_read_b128 v[226:229], v170 offset:55296
	ds_read_b128 v[230:233], v170 offset:56320
	global_load_lds_dwordx4 v[150:151], off
	s_add_i32 m0, s4, 0x2000
	s_add_u32 s44, s44, 0x80080
	v_lshl_add_u64 v[150:151], v[234:235], 0, s[12:13]
	s_addc_u32 s45, s45, 0
	s_add_i32 s4, s5, s53
	global_load_lds_dwordx4 v[150:151], off
	v_lshl_add_u64 v[150:151], s[44:45], 0, v[130:131]
	s_mov_b32 m0, s4
	s_nop 0
	global_load_lds_dwordx4 v[150:151], off
	v_lshl_add_u64 v[150:151], s[44:45], 0, v[134:135]
	s_add_i32 m0, s4, 0x2000
	s_nop 0
	global_load_lds_dwordx4 v[150:151], off
	v_lshl_add_u64 v[150:151], v[236:237], 0, s[12:13]
	s_mov_b32 m0, s60
	s_nop 0
	global_load_lds_dwordx4 v[150:151], off
	v_lshl_add_u64 v[150:151], v[238:239], 0, s[12:13]
	s_mov_b32 m0, s61
	s_nop 0
	global_load_lds_dwordx4 v[150:151], off
	s_waitcnt vmcnt(8)
	s_waitcnt lgkmcnt(0)
	s_barrier
	s_setprio 1
	s_waitcnt lgkmcnt(0)
	v_mfma_f32_16x16x32_bf16 v[60:63], v[146:149], v[200:203], v[60:63]
	v_mfma_f32_16x16x32_bf16 v[56:59], v[176:179], v[200:203], v[56:59]
	v_mfma_f32_16x16x32_bf16 v[44:47], v[146:149], v[208:211], v[44:47]
	v_mfma_f32_16x16x32_bf16 v[40:43], v[176:179], v[208:211], v[40:43]
	v_mfma_f32_16x16x32_bf16 v[28:31], v[146:149], v[218:221], v[28:31]
	v_mfma_f32_16x16x32_bf16 v[24:27], v[176:179], v[218:221], v[24:27]
	v_mfma_f32_16x16x32_bf16 v[12:15], v[146:149], v[226:229], v[12:15]
	v_mfma_f32_16x16x32_bf16 v[8:11], v[176:179], v[226:229], v[8:11]
	v_mfma_f32_16x16x32_bf16 v[60:63], v[172:175], v[204:207], v[60:63]
	v_mfma_f32_16x16x32_bf16 v[56:59], v[180:183], v[204:207], v[56:59]
	v_mfma_f32_16x16x32_bf16 v[44:47], v[172:175], v[212:215], v[44:47]
	v_mfma_f32_16x16x32_bf16 v[40:43], v[180:183], v[212:215], v[40:43]
	v_mfma_f32_16x16x32_bf16 v[28:31], v[172:175], v[222:225], v[28:31]
	v_mfma_f32_16x16x32_bf16 v[24:27], v[180:183], v[222:225], v[24:27]
	v_mfma_f32_16x16x32_bf16 v[12:15], v[172:175], v[230:233], v[12:15]
	v_mfma_f32_16x16x32_bf16 v[8:11], v[180:183], v[230:233], v[8:11]
	s_setprio 0
	s_setprio 1
	v_mfma_f32_16x16x32_bf16 v[52:55], v[184:187], v[200:203], v[52:55]
	v_mfma_f32_16x16x32_bf16 v[48:51], v[192:195], v[200:203], v[48:51]
	v_mfma_f32_16x16x32_bf16 v[36:39], v[184:187], v[208:211], v[36:39]
	v_mfma_f32_16x16x32_bf16 v[32:35], v[192:195], v[208:211], v[32:35]
	v_mfma_f32_16x16x32_bf16 v[20:23], v[184:187], v[218:221], v[20:23]
	v_mfma_f32_16x16x32_bf16 v[16:19], v[192:195], v[218:221], v[16:19]
	v_mfma_f32_16x16x32_bf16 v[4:7], v[184:187], v[226:229], v[4:7]
	v_mfma_f32_16x16x32_bf16 v[0:3], v[192:195], v[226:229], v[0:3]
	v_mfma_f32_16x16x32_bf16 v[52:55], v[188:191], v[204:207], v[52:55]
	v_mfma_f32_16x16x32_bf16 v[48:51], v[196:199], v[204:207], v[48:51]
	v_mfma_f32_16x16x32_bf16 v[36:39], v[188:191], v[212:215], v[36:39]
	v_mfma_f32_16x16x32_bf16 v[32:35], v[196:199], v[212:215], v[32:35]
	v_mfma_f32_16x16x32_bf16 v[20:23], v[188:191], v[222:225], v[20:23]
	v_mfma_f32_16x16x32_bf16 v[16:19], v[196:199], v[222:225], v[16:19]
	v_mfma_f32_16x16x32_bf16 v[4:7], v[188:191], v[230:233], v[4:7]
	v_mfma_f32_16x16x32_bf16 v[0:3], v[196:199], v[230:233], v[0:3]
	s_setprio 0
	s_barrier
	s_add_i32 s88, s88, 2
	s_add_u32 s42, s42, 0x100
	s_addc_u32 s43, s43, 0
	s_add_u32 s86, s86, 0x100
	s_addc_u32 s87, s87, 0
	s_cmp_gt_u32 s88, 29
	s_cbranch_scc1 .Lpeel_exit_4473

; #define PG8_BAR __builtin_amdgcn_s_barrier()
; template <class Epi, class Sched, bool ALIGN_EPI, bool I8 = false>
; __device__ __forceinline__ void gemm_phase(LAS unsigned char* lds, const Gemm g, const Sched& S, const Epi& E) {
;     ...
;         if constexpr (ALIGN_EPI) { if (wr == 0) PG8_BAR; }
.Lpeel_exit_4473:
	s_and_b64 vcc, exec, s[14:15]
	s_cbranch_vccz .LBB0_122
	s_barrier

; #define PG8_STAGE(bufoff, gbase, voff) do { _Pragma("unroll") for (int _i = 0; _i < 2; ++_i) \
;         __builtin_amdgcn_global_load_lds((const unsigned*)((const char*)(gbase) + (voff)[_i]), (LAS unsigned*)(lds + (bufoff) + ldsw + _i * 8192), 16, 0, 0); } while (0)
; #define PG8_LDA(dst, b, h) do { _Pragma("unroll") for (int m = 0; m < 4; ++m) _Pragma("unroll") for (int k = 0; k < 2; ++k) dst[m][k] = *(const LAS bf16x8*)(lds + PG8_SA(b, h) + aoff + m * 2048 + k * 1024); } while (0)
; #define PG8_BAR __builtin_amdgcn_s_barrier()
; template <class Epi, class Sched, bool ALIGN_EPI, bool I8 = false>
; __device__ __forceinline__ void gemm_phase(LAS unsigned char* lds, const Gemm g, const Sched& S, const Epi& E) {
;     ...
;         const bool has_next = S.next(ui + 1, nxt);
;         const char* nA = has_next ? (const char*)g.A + (size_t)nxt.z * g.zA + (size_t)nxt.pm * tstep : cA;
;         const char* nB = has_next ? (const char*)g.Bt + (size_t)nxt.z * g.zB + (size_t)nxt.pn * tstep : cB;
;         for (int t = 0; t < nt; t += 2) {
;             const bool last = (t == nt - 2);
;             const char* a1 = cA + (size_t)(t + 1) * kstep;
;             const char* a2 = last ? nA : cA + (size_t)(t + 2) * kstep; const char* b2 = last ? nB : cB + (size_t)(t + 2) * kstep;
;             const char* a3 = a2 + kstep; const char* b3 = b2 + kstep;
;             PG8_LDB(B0, 0, 0); PG8_LDB(B1, 0, 1); PG8_SCHED; PG8_LDA(At, 0, 0); PG8_STAGE(PG8_SA(1, 1), a1 + hstep, voffA);
;             PG8_WAIT_V(8); PG8_WAIT_L(0); PG8_BAR; PG8_MMA(0, 0, At, B0); PG8_MMA(0, 1, At, B1); PG8_BAR; PG8_SCHED;
;             PG8_LDA(At, 0, 1); PG8_STAGE(PG8_SB(0, 0), b2, voffB); PG8_STAGE(PG8_SB(0, 1), b2 + hstep, voffB); PG8_STAGE(PG8_SA(0, 0), a2, voffA);
;             PG8_WAIT_V(8); PG8_WAIT_L(0); PG8_BAR; PG8_MMA(1, 0, At, B0); PG8_MMA(1, 1, At, B1); PG8_BAR; PG8_SCHED;
;             PG8_LDB(B0, 1, 0); PG8_LDB(B1, 1, 1); PG8_SCHED; PG8_LDA(At, 1, 0); PG8_STAGE(PG8_SA(0, 1), a2 + hstep, voffA);
;             PG8_WAIT_V(8); PG8_WAIT_L(0); PG8_BAR; PG8_MMA(0, 0, At, B0); PG8_MMA(0, 1, At, B1); PG8_BAR; PG8_SCHED;
;             PG8_LDA(At, 1, 1); PG8_STAGE(PG8_SB(1, 0), b3, voffB); PG8_STAGE(PG8_SB(1, 1), b3 + hstep, voffB); PG8_STAGE(PG8_SA(1, 0), a3, voffA);
;             PG8_WAIT_V(8); PG8_WAIT_L(0); PG8_BAR; PG8_MMA(1, 0, At, B0); PG8_MMA(1, 1, At, B1); PG8_BAR; PG8_SCHED;
.LBB0_142:
	s_ashr_i32 s47, s46, 31
	s_lshl_b64 s[48:49], s[46:47], 19
	s_add_u32 s48, s27, s48
	s_addc_u32 s49, s39, s49
	s_and_b64 s[50:51], s[2:3], exec
	s_cselect_b32 s47, s49, s53
	s_cselect_b32 s55, s48, s52
	s_ashr_i32 s45, s44, 31
	s_lshl_b64 s[50:51], s[44:45], 19
	s_add_u32 s50, s41, s50
	s_addc_u32 s51, s43, s51
	s_and_b64 s[58:59], s[2:3], exec
	s_cselect_b32 s45, s51, s57
	s_cselect_b32 s61, s50, s56
	s_add_u32 s52, s52, 0x40080
	s_addc_u32 s53, s53, 0
	s_add_u32 s62, s56, 0x100
	s_addc_u32 s63, s57, 0
	s_mov_b32 vcc_lo, -2
	ds_read_b128 v[128:131], v225
	ds_read_b128 v[132:135], v225 offset:1024
	ds_read_b128 v[136:139], v225 offset:2048
	ds_read_b128 v[140:143], v225 offset:3072
	ds_read_b128 v[164:167], v226
	ds_read_b128 v[168:171], v226 offset:1024
	ds_read_b128 v[172:175], v226 offset:2048
	ds_read_b128 v[176:179], v226 offset:3072
	s_add_u32 s4, s52, 0xfffc0080
	s_addc_u32 s5, s53, -1
	s_cmp_eq_u32 vcc_lo, 12
	s_cselect_b32 s59, s47, s5
	s_cselect_b32 s58, s55, s4
	s_cselect_b32 s57, s45, s63
	s_cselect_b32 s56, s61, s62
	v_lshl_add_u64 v[212:213], s[52:53], 0, v[156:157]
	s_add_i32 m0, s67, 0xc000
	ds_read_b128 v[180:183], v227
	ds_read_b128 v[184:187], v227 offset:1024
	ds_read_b128 v[188:191], v227 offset:2048
	ds_read_b128 v[192:195], v227 offset:3072
	ds_read_b128 v[196:199], v227 offset:4096
	ds_read_b128 v[200:203], v227 offset:5120
	ds_read_b128 v[204:207], v227 offset:6144
	ds_read_b128 v[208:211], v227 offset:7168
	global_load_lds_dwordx4 v[212:213], off
	v_lshl_add_u64 v[212:213], s[52:53], 0, v[158:159]
	s_add_i32 m0, s67, 0xe000
	s_nop 0
	global_load_lds_dwordx4 v[212:213], off
	s_waitcnt vmcnt(8)
	s_waitcnt lgkmcnt(0)
	s_barrier
	s_setprio 1
	s_waitcnt lgkmcnt(0)
	v_mfma_i32_16x16x64_i8 v[124:127], v[128:131], v[180:183], 0
	v_mfma_i32_16x16x64_i8 v[120:123], v[136:139], v[180:183], 0
	v_mfma_i32_16x16x64_i8 v[108:111], v[128:131], v[188:191], 0
	v_mfma_i32_16x16x64_i8 v[104:107], v[136:139], v[188:191], 0
	v_mfma_i32_16x16x64_i8 v[92:95], v[128:131], v[196:199], 0
	v_mfma_i32_16x16x64_i8 v[88:91], v[136:139], v[196:199], 0
	v_mfma_i32_16x16x64_i8 v[76:79], v[128:131], v[204:207], 0
	v_mfma_i32_16x16x64_i8 v[72:75], v[136:139], v[204:207], 0
	v_mfma_i32_16x16x64_i8 v[124:127], v[132:135], v[184:187], v[124:127]
	v_mfma_i32_16x16x64_i8 v[120:123], v[140:143], v[184:187], v[120:123]
	v_mfma_i32_16x16x64_i8 v[108:111], v[132:135], v[192:195], v[108:111]
	v_mfma_i32_16x16x64_i8 v[104:107], v[140:143], v[192:195], v[104:107]
	v_mfma_i32_16x16x64_i8 v[92:95], v[132:135], v[200:203], v[92:95]
	v_mfma_i32_16x16x64_i8 v[88:91], v[140:143], v[200:203], v[88:91]
	v_mfma_i32_16x16x64_i8 v[76:79], v[132:135], v[208:211], v[76:79]
	v_mfma_i32_16x16x64_i8 v[72:75], v[140:143], v[208:211], v[72:75]
	s_setprio 0
	s_setprio 1
	v_mfma_i32_16x16x64_i8 v[116:119], v[164:167], v[180:183], 0
	v_mfma_i32_16x16x64_i8 v[112:115], v[172:175], v[180:183], 0
	v_mfma_i32_16x16x64_i8 v[100:103], v[164:167], v[188:191], 0
	v_mfma_i32_16x16x64_i8 v[96:99], v[172:175], v[188:191], 0
	v_mfma_i32_16x16x64_i8 v[84:87], v[164:167], v[196:199], 0
	v_mfma_i32_16x16x64_i8 v[80:83], v[172:175], v[196:199], 0
	v_mfma_i32_16x16x64_i8 v[68:71], v[164:167], v[204:207], 0
	v_mfma_i32_16x16x64_i8 v[64:67], v[172:175], v[204:207], 0
	v_mfma_i32_16x16x64_i8 v[116:119], v[168:171], v[184:187], v[116:119]
	v_mfma_i32_16x16x64_i8 v[112:115], v[176:179], v[184:187], v[112:115]
	v_mfma_i32_16x16x64_i8 v[100:103], v[168:171], v[192:195], v[100:103]
	v_mfma_i32_16x16x64_i8 v[96:99], v[176:179], v[192:195], v[96:99]
	v_mfma_i32_16x16x64_i8 v[84:87], v[168:171], v[200:203], v[84:87]
	v_mfma_i32_16x16x64_i8 v[80:83], v[176:179], v[200:203], v[80:83]
	v_mfma_i32_16x16x64_i8 v[68:71], v[168:171], v[208:211], v[68:71]
	v_mfma_i32_16x16x64_i8 v[64:67], v[176:179], v[208:211], v[64:67]
	s_setprio 0
	s_barrier
	s_add_i32 s4, s79, s64
	v_lshl_add_u64 v[212:213], s[56:57], 0, v[148:149]
	s_mov_b32 m0, s4
	ds_read_b128 v[180:183], v227 offset:16384
	ds_read_b128 v[184:187], v227 offset:17408
	ds_read_b128 v[188:191], v227 offset:18432
	ds_read_b128 v[192:195], v227 offset:19456
	ds_read_b128 v[196:199], v227 offset:20480
	ds_read_b128 v[200:203], v227 offset:21504
	ds_read_b128 v[204:207], v227 offset:22528
	ds_read_b128 v[208:211], v227 offset:23552
	global_load_lds_dwordx4 v[212:213], off
	s_add_i32 m0, s4, 0x2000
	s_add_u32 s4, s56, 0x40000
	v_lshl_add_u64 v[214:215], s[56:57], 0, v[144:145]
	s_addc_u32 s5, s57, 0
	s_add_i32 vcc_hi, s80, s64
	global_load_lds_dwordx4 v[214:215], off
	v_lshl_add_u64 v[220:221], s[4:5], 0, v[148:149]
	s_mov_b32 m0, vcc_hi
	v_lshl_add_u64 v[228:229], s[58:59], 0, v[146:147]
	global_load_lds_dwordx4 v[220:221], off
	v_lshl_add_u64 v[220:221], s[4:5], 0, v[144:145]
	s_add_i32 m0, vcc_hi, 0x2000
	s_nop 0
	global_load_lds_dwordx4 v[220:221], off
	v_lshl_add_u64 v[220:221], s[58:59], 0, v[150:151]
	s_mov_b32 m0, s67
	s_nop 0
	global_load_lds_dwordx4 v[220:221], off
	s_mov_b32 m0, s68
	s_nop 0
	global_load_lds_dwordx4 v[228:229], off
	s_waitcnt vmcnt(8)
	s_waitcnt lgkmcnt(0)
	s_barrier
; #define PG8_STAGE(bufoff, gbase, voff) do { _Pragma("unroll") for (int _i = 0; _i < 2; ++_i) \
;         __builtin_amdgcn_global_load_lds((const unsigned*)((const char*)(gbase) + (voff)[_i]), (LAS unsigned*)(lds + (bufoff) + ldsw + _i * 8192), 16, 0, 0); } while (0)
; #define PG8_LDA(dst, b, h) do { _Pragma("unroll") for (int m = 0; m < 4; ++m) _Pragma("unroll") for (int k = 0; k < 2; ++k) dst[m][k] = *(const LAS bf16x8*)(lds + PG8_SA(b, h) + aoff + m * 2048 + k * 1024); } while (0)
; #define PG8_LDB(dst, b, h) do { _Pragma("unroll") for (int n = 0; n < 2; ++n) _Pragma("unroll") for (int k = 0; k < 2; ++k) dst[n][k] = *(const LAS bf16x8*)(lds + PG8_SB(b, h) + boff + n * 2048 + k * 1024); } while (0)
; #define PG8_WAIT_V(n) asm volatile("s_waitcnt vmcnt(" #n ")" ::: "memory")
; #define PG8_WAIT_L(n) asm volatile("s_waitcnt lgkmcnt(" #n ")" ::: "memory")
; #define PG8_BAR __builtin_amdgcn_s_barrier()
; #define PG8_SCHED __builtin_amdgcn_sched_barrier(0)
; template <class Epi, class Sched, bool ALIGN_EPI, bool I8 = false>
; __device__ __forceinline__ void gemm_phase(LAS unsigned char* lds, const Gemm g, const Sched& S, const Epi& E) {
;     ...
;             PG8_WAIT_V(8); PG8_WAIT_L(0); PG8_BAR; PG8_MMA(1, 0, At, B0); PG8_MMA(1, 1, At, B1); PG8_BAR; PG8_SCHED;
;             PG8_LDB(B0, 1, 0); PG8_LDB(B1, 1, 1); PG8_SCHED; PG8_LDA(At, 1, 0); PG8_STAGE(PG8_SA(0, 1), a2 + hstep, voffA);
;             PG8_WAIT_V(8); PG8_WAIT_L(0); PG8_BAR; PG8_MMA(0, 0, At, B0); PG8_MMA(0, 1, At, B1); PG8_BAR; PG8_SCHED;
	s_setprio 1
	s_waitcnt lgkmcnt(0)
	v_mfma_i32_16x16x64_i8 v[60:63], v[128:131], v[180:183], 0
	v_mfma_i32_16x16x64_i8 v[56:59], v[136:139], v[180:183], 0
	v_mfma_i32_16x16x64_i8 v[44:47], v[128:131], v[188:191], 0
	v_mfma_i32_16x16x64_i8 v[40:43], v[136:139], v[188:191], 0
	v_mfma_i32_16x16x64_i8 v[28:31], v[128:131], v[196:199], 0
	v_mfma_i32_16x16x64_i8 v[24:27], v[136:139], v[196:199], 0
	v_mfma_i32_16x16x64_i8 v[12:15], v[128:131], v[204:207], 0
	v_mfma_i32_16x16x64_i8 v[8:11], v[136:139], v[204:207], 0
	v_mfma_i32_16x16x64_i8 v[60:63], v[132:135], v[184:187], v[60:63]
	v_mfma_i32_16x16x64_i8 v[56:59], v[140:143], v[184:187], v[56:59]
	v_mfma_i32_16x16x64_i8 v[44:47], v[132:135], v[192:195], v[44:47]
	v_mfma_i32_16x16x64_i8 v[40:43], v[140:143], v[192:195], v[40:43]
	v_mfma_i32_16x16x64_i8 v[28:31], v[132:135], v[200:203], v[28:31]
	v_mfma_i32_16x16x64_i8 v[24:27], v[140:143], v[200:203], v[24:27]
	v_mfma_i32_16x16x64_i8 v[12:15], v[132:135], v[208:211], v[12:15]
	v_mfma_i32_16x16x64_i8 v[8:11], v[140:143], v[208:211], v[8:11]
	s_setprio 0
	s_setprio 1
	v_mfma_i32_16x16x64_i8 v[52:55], v[164:167], v[180:183], 0
	v_mfma_i32_16x16x64_i8 v[48:51], v[172:175], v[180:183], 0
	v_mfma_i32_16x16x64_i8 v[36:39], v[164:167], v[188:191], 0
	v_mfma_i32_16x16x64_i8 v[32:35], v[172:175], v[188:191], 0
	v_mfma_i32_16x16x64_i8 v[20:23], v[164:167], v[196:199], 0
	v_mfma_i32_16x16x64_i8 v[16:19], v[172:175], v[196:199], 0
	v_mfma_i32_16x16x64_i8 v[4:7], v[164:167], v[204:207], 0
	v_mfma_i32_16x16x64_i8 v[0:3], v[172:175], v[204:207], 0
	v_mfma_i32_16x16x64_i8 v[52:55], v[168:171], v[184:187], v[52:55]
	v_mfma_i32_16x16x64_i8 v[48:51], v[176:179], v[184:187], v[48:51]
	v_mfma_i32_16x16x64_i8 v[36:39], v[168:171], v[192:195], v[36:39]
	v_mfma_i32_16x16x64_i8 v[32:35], v[176:179], v[192:195], v[32:35]
	v_mfma_i32_16x16x64_i8 v[20:23], v[168:171], v[200:203], v[20:23]
	v_mfma_i32_16x16x64_i8 v[16:19], v[176:179], v[200:203], v[16:19]
	v_mfma_i32_16x16x64_i8 v[4:7], v[168:171], v[208:211], v[4:7]
	v_mfma_i32_16x16x64_i8 v[0:3], v[176:179], v[208:211], v[0:3]
	s_setprio 0
	s_barrier
	s_add_i32 vcc_hi, 0, 0x18000
	s_add_i32 s7, 0, 0x1c000
	v_add_u32_e32 v140, vcc_hi, v222
	v_add_u32_e32 v152, s7, v222
	ds_read_b128 v[128:131], v140
	ds_read_b128 v[132:135], v140 offset:1024
	ds_read_b128 v[136:139], v140 offset:2048
	ds_read_b128 v[140:143], v140 offset:3072
	ds_read_b128 v[164:167], v152
	ds_read_b128 v[168:171], v152 offset:1024
	ds_read_b128 v[172:175], v152 offset:2048
	ds_read_b128 v[176:179], v152 offset:3072
	s_add_u32 s4, s58, 0x40000
	s_addc_u32 s5, s59, 0
	s_mov_b32 m0, s69
	v_lshl_add_u64 v[230:231], s[4:5], 0, v[150:151]
	ds_read_b128 v[180:183], v227 offset:32768
	ds_read_b128 v[184:187], v227 offset:33792
	ds_read_b128 v[188:191], v227 offset:34816
	ds_read_b128 v[192:195], v227 offset:35840
	ds_read_b128 v[196:199], v227 offset:36864
	ds_read_b128 v[200:203], v227 offset:37888
	ds_read_b128 v[204:207], v227 offset:38912
	ds_read_b128 v[208:211], v227 offset:39936
	global_load_lds_dwordx4 v[230:231], off
	v_lshl_add_u64 v[230:231], s[4:5], 0, v[146:147]
	s_mov_b32 m0, s70
	s_nop 0
	global_load_lds_dwordx4 v[230:231], off
	s_waitcnt vmcnt(8)
	s_waitcnt lgkmcnt(0)
	s_barrier
	s_setprio 1
	s_waitcnt lgkmcnt(0)
	v_mfma_i32_16x16x64_i8 v[124:127], v[128:131], v[180:183], v[124:127]
	v_mfma_i32_16x16x64_i8 v[120:123], v[136:139], v[180:183], v[120:123]
	v_mfma_i32_16x16x64_i8 v[108:111], v[128:131], v[188:191], v[108:111]
	v_mfma_i32_16x16x64_i8 v[104:107], v[136:139], v[188:191], v[104:107]
	v_mfma_i32_16x16x64_i8 v[92:95], v[128:131], v[196:199], v[92:95]
	v_mfma_i32_16x16x64_i8 v[88:91], v[136:139], v[196:199], v[88:91]
	v_mfma_i32_16x16x64_i8 v[76:79], v[128:131], v[204:207], v[76:79]
	v_mfma_i32_16x16x64_i8 v[72:75], v[136:139], v[204:207], v[72:75]
	v_mfma_i32_16x16x64_i8 v[124:127], v[132:135], v[184:187], v[124:127]
	v_mfma_i32_16x16x64_i8 v[120:123], v[140:143], v[184:187], v[120:123]
	v_mfma_i32_16x16x64_i8 v[108:111], v[132:135], v[192:195], v[108:111]
	v_mfma_i32_16x16x64_i8 v[104:107], v[140:143], v[192:195], v[104:107]
	v_mfma_i32_16x16x64_i8 v[92:95], v[132:135], v[200:203], v[92:95]
	v_mfma_i32_16x16x64_i8 v[88:91], v[140:143], v[200:203], v[88:91]
	v_mfma_i32_16x16x64_i8 v[76:79], v[132:135], v[208:211], v[76:79]
	v_mfma_i32_16x16x64_i8 v[72:75], v[140:143], v[208:211], v[72:75]
	s_setprio 0
	s_setprio 1
	v_mfma_i32_16x16x64_i8 v[116:119], v[164:167], v[180:183], v[116:119]
	v_mfma_i32_16x16x64_i8 v[112:115], v[172:175], v[180:183], v[112:115]
	v_mfma_i32_16x16x64_i8 v[100:103], v[164:167], v[188:191], v[100:103]
	v_mfma_i32_16x16x64_i8 v[96:99], v[172:175], v[188:191], v[96:99]
	v_mfma_i32_16x16x64_i8 v[84:87], v[164:167], v[196:199], v[84:87]
	v_mfma_i32_16x16x64_i8 v[80:83], v[172:175], v[196:199], v[80:83]
	v_mfma_i32_16x16x64_i8 v[68:71], v[164:167], v[204:207], v[68:71]
	v_mfma_i32_16x16x64_i8 v[64:67], v[172:175], v[204:207], v[64:67]
	v_mfma_i32_16x16x64_i8 v[116:119], v[168:171], v[184:187], v[116:119]
	v_mfma_i32_16x16x64_i8 v[112:115], v[176:179], v[184:187], v[112:115]
	v_mfma_i32_16x16x64_i8 v[100:103], v[168:171], v[192:195], v[100:103]
	v_mfma_i32_16x16x64_i8 v[96:99], v[176:179], v[192:195], v[96:99]
	v_mfma_i32_16x16x64_i8 v[84:87], v[168:171], v[200:203], v[84:87]
	v_mfma_i32_16x16x64_i8 v[80:83], v[176:179], v[200:203], v[80:83]
	v_mfma_i32_16x16x64_i8 v[68:71], v[168:171], v[208:211], v[68:71]
	v_mfma_i32_16x16x64_i8 v[64:67], v[176:179], v[208:211], v[64:67]
	s_setprio 0
	s_barrier
; #define PG8_STAGE(bufoff, gbase, voff) do { _Pragma("unroll") for (int _i = 0; _i < 2; ++_i) \
;         __builtin_amdgcn_global_load_lds((const unsigned*)((const char*)(gbase) + (voff)[_i]), (LAS unsigned*)(lds + (bufoff) + ldsw + _i * 8192), 16, 0, 0); } while (0)
; #define PG8_LDA(dst, b, h) do { _Pragma("unroll") for (int m = 0; m < 4; ++m) _Pragma("unroll") for (int k = 0; k < 2; ++k) dst[m][k] = *(const LAS bf16x8*)(lds + PG8_SA(b, h) + aoff + m * 2048 + k * 1024); } while (0)
; #define PG8_WAIT_V(n) asm volatile("s_waitcnt vmcnt(" #n ")" ::: "memory")
; #define PG8_WAIT_L(n) asm volatile("s_waitcnt lgkmcnt(" #n ")" ::: "memory")
; #define PG8_BAR __builtin_amdgcn_s_barrier()
; #define PG8_SCHED __builtin_amdgcn_sched_barrier(0)
; template <class Epi, class Sched, bool ALIGN_EPI, bool I8 = false>
; __device__ __forceinline__ void gemm_phase(LAS unsigned char* lds, const Gemm g, const Sched& S, const Epi& E) {
;     ...
;             PG8_LDA(At, 1, 1); PG8_STAGE(PG8_SB(1, 0), b3, voffB); PG8_STAGE(PG8_SB(1, 1), b3 + hstep, voffB); PG8_STAGE(PG8_SA(1, 0), a3, voffA);
;             PG8_WAIT_V(8); PG8_WAIT_L(0); PG8_BAR; PG8_MMA(1, 0, At, B0); PG8_MMA(1, 1, At, B1); PG8_BAR; PG8_SCHED;
;         }
	s_add_i32 s4, vcc_hi, s64
	v_lshl_add_u64 v[212:213], v[212:213], 0, s[18:19]
	s_mov_b32 m0, s4
	ds_read_b128 v[180:183], v227 offset:49152
	ds_read_b128 v[184:187], v227 offset:50176
	ds_read_b128 v[188:191], v227 offset:51200
	ds_read_b128 v[192:195], v227 offset:52224
	ds_read_b128 v[196:199], v227 offset:53248
	ds_read_b128 v[200:203], v227 offset:54272
	ds_read_b128 v[204:207], v227 offset:55296
	ds_read_b128 v[208:211], v227 offset:56320
	global_load_lds_dwordx4 v[212:213], off
	s_add_i32 m0, s4, 0x2000
	s_add_u32 s4, s56, 0x40080
	v_lshl_add_u64 v[212:213], v[214:215], 0, s[18:19]
	s_addc_u32 s5, s57, 0
	s_add_i32 s7, s7, s64
	global_load_lds_dwordx4 v[212:213], off
	v_lshl_add_u64 v[212:213], s[4:5], 0, v[148:149]
	s_mov_b32 m0, s7
	s_nop 0
	global_load_lds_dwordx4 v[212:213], off
	v_lshl_add_u64 v[212:213], s[4:5], 0, v[144:145]
	s_add_i32 m0, s7, 0x2000
	s_nop 0
	global_load_lds_dwordx4 v[212:213], off
	v_lshl_add_u64 v[212:213], v[220:221], 0, s[18:19]
	s_mov_b32 m0, s73
	s_nop 0
	global_load_lds_dwordx4 v[212:213], off
	v_lshl_add_u64 v[212:213], v[228:229], 0, s[18:19]
	s_mov_b32 m0, s74
	s_nop 0
	global_load_lds_dwordx4 v[212:213], off
	s_waitcnt vmcnt(8)
	s_waitcnt lgkmcnt(0)
	s_barrier
	s_setprio 1
	s_waitcnt lgkmcnt(0)
	v_mfma_i32_16x16x64_i8 v[60:63], v[128:131], v[180:183], v[60:63]
	v_mfma_i32_16x16x64_i8 v[56:59], v[136:139], v[180:183], v[56:59]
	v_mfma_i32_16x16x64_i8 v[44:47], v[128:131], v[188:191], v[44:47]
	v_mfma_i32_16x16x64_i8 v[40:43], v[136:139], v[188:191], v[40:43]
	v_mfma_i32_16x16x64_i8 v[28:31], v[128:131], v[196:199], v[28:31]
	v_mfma_i32_16x16x64_i8 v[24:27], v[136:139], v[196:199], v[24:27]
	v_mfma_i32_16x16x64_i8 v[12:15], v[128:131], v[204:207], v[12:15]
	v_mfma_i32_16x16x64_i8 v[8:11], v[136:139], v[204:207], v[8:11]
	v_mfma_i32_16x16x64_i8 v[60:63], v[132:135], v[184:187], v[60:63]
	v_mfma_i32_16x16x64_i8 v[56:59], v[140:143], v[184:187], v[56:59]
	v_mfma_i32_16x16x64_i8 v[44:47], v[132:135], v[192:195], v[44:47]
	v_mfma_i32_16x16x64_i8 v[40:43], v[140:143], v[192:195], v[40:43]
	v_mfma_i32_16x16x64_i8 v[28:31], v[132:135], v[200:203], v[28:31]
	v_mfma_i32_16x16x64_i8 v[24:27], v[140:143], v[200:203], v[24:27]
	v_mfma_i32_16x16x64_i8 v[12:15], v[132:135], v[208:211], v[12:15]
	v_mfma_i32_16x16x64_i8 v[8:11], v[140:143], v[208:211], v[8:11]
	s_setprio 0
	s_setprio 1
	v_mfma_i32_16x16x64_i8 v[52:55], v[164:167], v[180:183], v[52:55]
	v_mfma_i32_16x16x64_i8 v[48:51], v[172:175], v[180:183], v[48:51]
	v_mfma_i32_16x16x64_i8 v[36:39], v[164:167], v[188:191], v[36:39]
	v_mfma_i32_16x16x64_i8 v[32:35], v[172:175], v[188:191], v[32:35]
	v_mfma_i32_16x16x64_i8 v[20:23], v[164:167], v[196:199], v[20:23]
	v_mfma_i32_16x16x64_i8 v[16:19], v[172:175], v[196:199], v[16:19]
	v_mfma_i32_16x16x64_i8 v[4:7], v[164:167], v[204:207], v[4:7]
	v_mfma_i32_16x16x64_i8 v[0:3], v[172:175], v[204:207], v[0:3]
	v_mfma_i32_16x16x64_i8 v[52:55], v[168:171], v[184:187], v[52:55]
	v_mfma_i32_16x16x64_i8 v[48:51], v[176:179], v[184:187], v[48:51]
	v_mfma_i32_16x16x64_i8 v[36:39], v[168:171], v[192:195], v[36:39]
	v_mfma_i32_16x16x64_i8 v[32:35], v[176:179], v[192:195], v[32:35]
	v_mfma_i32_16x16x64_i8 v[20:23], v[168:171], v[200:203], v[20:23]
	v_mfma_i32_16x16x64_i8 v[16:19], v[176:179], v[200:203], v[16:19]
	v_mfma_i32_16x16x64_i8 v[4:7], v[168:171], v[208:211], v[4:7]
	v_mfma_i32_16x16x64_i8 v[0:3], v[176:179], v[208:211], v[0:3]
	s_setprio 0
	s_barrier
	s_add_i32 vcc_lo, vcc_lo, 2
	s_add_u32 s52, s52, 0x100
	s_addc_u32 s53, s53, 0
	s_add_u32 s62, s62, 0x100
	s_addc_u32 s63, s63, 0
	s_cmp_gt_u32 vcc_lo, 13
	s_cbranch_scc1 .Lpeel_exit_6244

; #define PG8_BAR __builtin_amdgcn_s_barrier()
; template <class Epi, class Sched, bool ALIGN_EPI, bool I8 = false>
; __device__ __forceinline__ void gemm_phase(LAS unsigned char* lds, const Gemm g, const Sched& S, const Epi& E) {
;     ...
;         if constexpr (ALIGN_EPI) { if (wr == 0) PG8_BAR; }
.Lpeel_exit_6244:
	s_and_b64 vcc, exec, s[24:25]
	s_cbranch_vccz .LBB0_146
	s_barrier

; #define LAS __attribute__((address_space(3)))
; __device__ __forceinline__ unsigned pk2(float lo, float hi) { f32x2 v = {lo, hi}; bf16x2_t b = __builtin_convertvector(v, bf16x2_t); return __builtin_bit_cast(unsigned, b); }
; #define MFMA32(a, b, c) __builtin_amdgcn_mfma_f32_32x32x16_bf16((a), (b), (c), 0, 0, 0)
; #define ATT_BAR() asm volatile("s_waitcnt lgkmcnt(0)\n\ts_barrier" ::: "memory")
; __device__ __forceinline__ void attn_item(const bf16_t* __restrict__ Q, const bf16_t* __restrict__ Kb, const bf16_t* __restrict__ VT, const bf16_t* __restrict__ GA, ...
;     ...
;         float ls = 0.f;
; #pragma unroll
;         for (int i = 0; i < 16; ++i) { s0[i] = __builtin_amdgcn_exp2f(s0[i]); s1[i] = __builtin_amdgcn_exp2f(s1[i]); ls += s0[i] + s1[i]; }
;         lrun += ls;
; #pragma unroll
;         for (int s = 0; s < 2; ++s) {
;             u32x4 pa, pb;
;             pa.x = pk2(s0[8 * s + 0], s0[8 * s + 1]); pa.y = pk2(s0[8 * s + 2], s0[8 * s + 3]); pa.z = pk2(s0[8 * s + 4], s0[8 * s + 5]); pa.w = pk2(s0[8 * s + 6], s0[8 * s + 7]);
;             pb.x = pk2(s1[8 * s + 0], s1[8 * s + 1]); pb.y = pk2(s1[8 * s + 2], s1[8 * s + 3]); pb.z = pk2(s1[8 * s + 4], s1[8 * s + 5]); pb.w = pk2(s1[8 * s + 6], s1[8 * s + 7]);
;             const bf16x8 va0 = *(const LAS bf16x8*)(vfp + 32 * s), va1 = *(const LAS bf16x8*)(vfp + 32 * ATP + 32 * s);
;             const bf16x8 vb0 = *(const LAS bf16x8*)(vfp + 64 + 32 * s), vb1 = *(const LAS bf16x8*)(vfp + 32 * ATP + 64 + 32 * s);
;             o0 = MFMA32(va0, __builtin_bit_cast(bf16x8, pa), o0); o1 = MFMA32(va1, __builtin_bit_cast(bf16x8, pa), o1);
;             o0 = MFMA32(vb0, __builtin_bit_cast(bf16x8, pb), o0); o1 = MFMA32(vb1, __builtin_bit_cast(bf16x8, pb), o1);
;         }
;         buf ^= 1;
; #pragma unroll
;         for (int i = 0; i < 8; ++i) *(LAS u32x4*)(pl + buf * ATT_WAVE_LDS + stoff + 8 * i * ATP) = tr[i];
;         tg += (j + 2 <= 8) ? tstep : (size_t)0;
; #pragma unroll
;         for (int i = 0; i < 8; ++i) tr[i] = *(const u32x4*)(tg + i * rstep);
;         ATT_BAR();
.LBB0_261:
	v_add3_u32 v190, s28, v165, v167
	s_xor_b32 s72, s72, 1
	s_mul_i32 s99, s72, 0x4800
	v_add_u32_e32 v226, s99, v186
	v_exp_f32_e32 v189, v50
	v_exp_f32_e32 v220, v51
	v_exp_f32_e32 v222, v52
	v_exp_f32_e32 v224, v53
	ds_read_b128 v[50:53], v190 offset:9216
	s_waitcnt vmcnt(1)
	ds_write_b128 v226, v[126:129]
	ds_write_b128 v226, v[122:125] offset:1152
	ds_write_b128 v226, v[106:109] offset:2304
	ds_write_b128 v226, v[118:121] offset:3456
	ds_write_b128 v226, v[102:105] offset:4608
	ds_write_b128 v226, v[114:117] offset:5760
	ds_write_b128 v226, v[98:101] offset:6912
	s_waitcnt vmcnt(0)
	ds_write_b128 v226, v[110:113] offset:8064
	v_exp_f32_e32 v195, v54
	v_exp_f32_e32 v194, v55
	v_exp_f32_e32 v199, v56
	v_exp_f32_e32 v198, v57
	v_exp_f32_e32 v203, v58
	v_exp_f32_e32 v202, v59
	v_pk_mov_b32 v[56:57], v[194:195], v[194:195] op_sel:[1,0]
	v_pk_mov_b32 v[58:59], v[198:199], v[198:199] op_sel:[1,0]
	v_cvt_pk_bf16_f32 v54, v189, v220
	v_cvt_pk_bf16_f32 v55, v222, v224
	v_cvt_pk_bf16_f32 v56, v56, v57
	v_cvt_pk_bf16_f32 v57, v58, v59
	v_exp_f32_e32 v197, v70
	v_exp_f32_e32 v196, v71
	s_waitcnt lgkmcnt(8)
	v_mfma_f32_32x32x16_bf16 v[2:17], v[50:53], v[54:57], v[2:17]
	v_exp_f32_e32 v201, v72
	v_exp_f32_e32 v200, v73
	v_exp_f32_e32 v216, v66
	v_exp_f32_e32 v221, v67
	v_exp_f32_e32 v223, v68
	v_exp_f32_e32 v225, v69
	v_exp_f32_e32 v207, v60
	v_exp_f32_e32 v206, v61
	v_exp_f32_e32 v211, v62
	v_exp_f32_e32 v210, v63
	v_exp_f32_e32 v215, v64
	v_exp_f32_e32 v214, v65
	ds_read_b128 v[58:61], v190 offset:9280
	ds_read_b128 v[62:65], v190 offset:9248
	v_pk_mov_b32 v[52:53], v[196:197], v[196:197] op_sel:[1,0]
	v_pk_mov_b32 v[66:67], v[200:201], v[200:201] op_sel:[1,0]
	v_cvt_pk_bf16_f32 v50, v216, v221
	v_cvt_pk_bf16_f32 v51, v223, v225
	v_cvt_pk_bf16_f32 v52, v52, v53
	v_cvt_pk_bf16_f32 v53, v66, v67
	v_pk_mov_b32 v[70:71], v[214:215], v[214:215] op_sel:[1,0]
	ds_read_b128 v[66:69], v190 offset:9312
	s_waitcnt lgkmcnt(2)
	v_mfma_f32_32x32x16_bf16 v[2:17], v[58:61], v[50:53], v[2:17]
	v_pk_mov_b32 v[58:59], v[202:203], v[202:203] op_sel:[1,0]
	v_pk_mov_b32 v[60:61], v[206:207], v[206:207] op_sel:[1,0]
	v_cvt_pk_bf16_f32 v58, v58, v59
	v_cvt_pk_bf16_f32 v59, v60, v61
	v_pk_mov_b32 v[60:61], v[210:211], v[210:211] op_sel:[1,0]
	v_exp_f32_e32 v205, v74
	v_cvt_pk_bf16_f32 v60, v60, v61
	v_cvt_pk_bf16_f32 v61, v70, v71
	v_exp_f32_e32 v204, v75
	v_exp_f32_e32 v209, v76
	s_waitcnt lgkmcnt(1)
	v_mfma_f32_32x32x16_bf16 v[2:17], v[62:65], v[58:61], v[2:17]
	v_exp_f32_e32 v208, v77
	v_exp_f32_e32 v213, v78
	v_exp_f32_e32 v212, v79
	v_exp_f32_e32 v219, v80
	v_exp_f32_e32 v218, v81
	v_pk_mov_b32 v[70:71], v[204:205], v[204:205] op_sel:[1,0]
	v_pk_mov_b32 v[72:73], v[208:209], v[208:209] op_sel:[1,0]
	s_add_i32 s70, s33, 1
	v_cvt_pk_bf16_f32 v70, v70, v71
	v_cvt_pk_bf16_f32 v71, v72, v73
	v_pk_mov_b32 v[72:73], v[212:213], v[212:213] op_sel:[1,0]
	v_pk_mov_b32 v[62:63], v[218:219], v[218:219] op_sel:[1,0]
	v_cvt_pk_bf16_f32 v72, v72, v73
	v_cvt_pk_bf16_f32 v73, v62, v63
	s_cmp_lt_i32 s33, 6
	s_waitcnt lgkmcnt(0)
	v_mfma_f32_32x32x16_bf16 v[2:17], v[66:69], v[70:73], v[2:17]
	s_cselect_b32 s7, s64, 0
	s_lshl_b32 s28, s7, 1
	v_lshl_add_u64 v[152:153], v[152:153], 0, s[28:29]
	s_mov_b32 s67, s29
	ds_read_b128 v[62:65], v190 offset:13824
	ds_read_b128 v[74:77], v190 offset:13856
	ds_read_b128 v[78:81], v190 offset:13888
	ds_read_b128 v[190:193], v190 offset:13920
	v_lshl_add_u64 v[66:67], v[152:153], 0, s[66:67]
	v_lshl_add_u64 v[68:69], v[66:67], 0, s[68:69]
	global_load_dwordx4 v[122:125], v[66:67], off
	global_load_dwordx4 v[106:109], v[68:69], off
	v_lshl_add_u64 v[66:67], v[68:69], 0, s[68:69]
	v_lshl_add_u64 v[68:69], v[66:67], 0, s[68:69]
	global_load_dwordx4 v[118:121], v[66:67], off
	global_load_dwordx4 v[102:105], v[68:69], off
	v_lshl_add_u64 v[66:67], v[68:69], 0, s[68:69]
	v_lshl_add_u64 v[68:69], v[66:67], 0, s[68:69]
	global_load_dwordx4 v[114:117], v[66:67], off
	global_load_dwordx4 v[98:101], v[68:69], off
	v_lshl_add_u64 v[66:67], v[68:69], 0, s[68:69]
	global_load_dwordx4 v[126:129], v[152:153], off
	global_load_dwordx4 v[110:113], v[66:67], off
	s_waitcnt lgkmcnt(3)
	v_mfma_f32_32x32x16_bf16 v[18:33], v[62:65], v[54:57], v[18:33]
	v_add_f32_e32 v189, v216, v189
	v_add_f32_e32 v216, v221, v220
	v_add_f32_e32 v189, 0, v189
	v_add_f32_e32 v220, v223, v222
	v_add_f32_e32 v189, v216, v189
	v_add_f32_e32 v221, v225, v224
	v_pk_add_f32 v[66:67], v[196:197], v[194:195]
	s_waitcnt lgkmcnt(1)
	v_mfma_f32_32x32x16_bf16 v[18:33], v[78:81], v[50:53], v[18:33]
	v_add_f32_e32 v50, v220, v189
	v_add_f32_e32 v50, v221, v50
	v_add_f32_e32 v50, v67, v50
	v_add_f32_e64 v54, v200, v198
	v_add_f32_e64 v55, v201, v199
	v_add_f32_e32 v50, v66, v50
	v_add_f32_e32 v50, v55, v50
	v_pk_add_f32 v[56:57], v[204:205], v[202:203]
	v_mfma_f32_32x32x16_bf16 v[18:33], v[74:77], v[58:61], v[18:33]
	v_add_f32_e32 v50, v54, v50
	v_add_f32_e32 v50, v57, v50
	v_add_f32_e64 v62, v208, v206
	v_add_f32_e64 v63, v209, v207
	v_add_f32_e32 v50, v56, v50
	v_add_f32_e32 v50, v63, v50
	v_pk_add_f32 v[64:65], v[212:213], v[210:211]
	v_add_f32_e32 v50, v62, v50
	s_waitcnt lgkmcnt(0)
	v_mfma_f32_32x32x16_bf16 v[18:33], v[190:193], v[70:73], v[18:33]
	v_add_f32_e32 v50, v65, v50
	v_add_f32_e64 v68, v218, v214
	v_add_f32_e64 v69, v219, v215
	v_add_f32_e32 v50, v64, v50
	v_add_f32_e32 v50, v69, v50
	s_waitcnt lgkmcnt(0)
	s_barrier
	v_add_f32_e32 v50, v68, v50
	v_add_f32_e32 v187, v187, v50
	s_cmp_lt_i32 s33, 7
	v_add_u32_e32 v188, 0xffffff00, v188
	s_cbranch_scc0 .LBB0_217
	s_mov_b32 s33, s70
	s_branch .LBB0_255

; #define PG8_STAGE(bufoff, gbase, voff) do { _Pragma("unroll") for (int _i = 0; _i < 2; ++_i) \
;         __builtin_amdgcn_global_load_lds((const unsigned*)((const char*)(gbase) + (voff)[_i]), (LAS unsigned*)(lds + (bufoff) + ldsw + _i * 8192), 16, 0, 0); } while (0)
; #define PG8_LDA(dst, b, h) do { _Pragma("unroll") for (int m = 0; m < 4; ++m) _Pragma("unroll") for (int k = 0; k < 2; ++k) dst[m][k] = *(const LAS bf16x8*)(lds + PG8_SA(b, h) + aoff + m * 2048 + k * 1024); } while (0)
; #define PG8_BAR __builtin_amdgcn_s_barrier()
; template <class Epi, class Sched, bool ALIGN_EPI, bool I8 = false>
; __device__ __forceinline__ void gemm_phase(LAS unsigned char* lds, const Gemm g, const Sched& S, const Epi& E) {
;     ...
;         const bool has_next = S.next(ui + 1, nxt);
;         const char* nA = has_next ? (const char*)g.A + (size_t)nxt.z * g.zA + (size_t)nxt.pm * tstep : cA;
;         const char* nB = has_next ? (const char*)g.Bt + (size_t)nxt.z * g.zB + (size_t)nxt.pn * tstep : cB;
;         for (int t = 0; t < nt; t += 2) {
;             const bool last = (t == nt - 2);
;             const char* a1 = cA + (size_t)(t + 1) * kstep;
;             const char* a2 = last ? nA : cA + (size_t)(t + 2) * kstep; const char* b2 = last ? nB : cB + (size_t)(t + 2) * kstep;
;             const char* a3 = a2 + kstep; const char* b3 = b2 + kstep;
;             PG8_LDB(B0, 0, 0); PG8_LDB(B1, 0, 1); PG8_SCHED; PG8_LDA(At, 0, 0); PG8_STAGE(PG8_SA(1, 1), a1 + hstep, voffA);
;             PG8_WAIT_V(8); PG8_WAIT_L(0); PG8_BAR; PG8_MMA(0, 0, At, B0); PG8_MMA(0, 1, At, B1); PG8_BAR; PG8_SCHED;
;             PG8_LDA(At, 0, 1); PG8_STAGE(PG8_SB(0, 0), b2, voffB); PG8_STAGE(PG8_SB(0, 1), b2 + hstep, voffB); PG8_STAGE(PG8_SA(0, 0), a2, voffA);
;             PG8_WAIT_V(8); PG8_WAIT_L(0); PG8_BAR; PG8_MMA(1, 0, At, B0); PG8_MMA(1, 1, At, B1); PG8_BAR; PG8_SCHED;
;             PG8_LDB(B0, 1, 0); PG8_LDB(B1, 1, 1); PG8_SCHED; PG8_LDA(At, 1, 0); PG8_STAGE(PG8_SA(0, 1), a2 + hstep, voffA);
;             PG8_WAIT_V(8); PG8_WAIT_L(0); PG8_BAR; PG8_MMA(0, 0, At, B0); PG8_MMA(0, 1, At, B1); PG8_BAR; PG8_SCHED;
;             PG8_LDA(At, 1, 1); PG8_STAGE(PG8_SB(1, 0), b3, voffB); PG8_STAGE(PG8_SB(1, 1), b3 + hstep, voffB); PG8_STAGE(PG8_SA(1, 0), a3, voffA);
;             PG8_WAIT_V(8); PG8_WAIT_L(0); PG8_BAR; PG8_MMA(1, 0, At, B0); PG8_MMA(1, 1, At, B1); PG8_BAR; PG8_SCHED;
.LBB0_411:
	s_ashr_i32 s35, s34, 31
	s_lshl_b64 s[36:37], s[34:35], 20
	s_add_u32 s36, s46, s36
	s_addc_u32 s37, s47, s37
	s_and_b64 s[38:39], s[2:3], exec
	s_cselect_b32 s35, s37, s41
	s_cselect_b32 s65, s36, s40
	s_ashr_i32 s31, s30, 31
	s_lshl_b64 s[38:39], s[30:31], 20
	s_add_u32 s38, s48, s38
	s_addc_u32 s39, s49, s39
	s_and_b64 s[44:45], s[2:3], exec
	s_cselect_b32 s31, s39, s43
	s_cselect_b32 s66, s38, s42
	s_add_u32 s40, s40, 0x80080
	s_addc_u32 s41, s41, 0
	s_add_u32 s67, s42, 0x100
	s_addc_u32 s68, s43, 0
	s_mov_b32 s69, -2
	ds_read_b128 v[150:153], v147
	ds_read_b128 v[154:157], v147 offset:1024
	ds_read_b128 v[158:161], v147 offset:2048
	ds_read_b128 v[162:165], v147 offset:3072
	ds_read_b128 v[166:169], v148
	ds_read_b128 v[170:173], v148 offset:1024
	ds_read_b128 v[174:177], v148 offset:2048
	ds_read_b128 v[178:181], v148 offset:3072
	s_add_u32 s7, s40, 0xfff80080
	s_addc_u32 s42, s41, -1
	s_cmp_eq_u32 s69, 28
	s_cselect_b32 s45, s35, s42
	s_cselect_b32 s44, s65, s7
	s_cselect_b32 s43, s31, s68
	s_cselect_b32 s42, s66, s67
	v_lshl_add_u64 v[214:215], s[40:41], 0, v[136:137]
	s_add_i32 m0, s29, 0xc000
	ds_read_b128 v[182:185], v149
	ds_read_b128 v[186:189], v149 offset:1024
	ds_read_b128 v[190:193], v149 offset:2048
	ds_read_b128 v[194:197], v149 offset:3072
	ds_read_b128 v[198:201], v149 offset:4096
	ds_read_b128 v[202:205], v149 offset:5120
	ds_read_b128 v[206:209], v149 offset:6144
	ds_read_b128 v[210:213], v149 offset:7168
	global_load_lds_dwordx4 v[214:215], off
	v_lshl_add_u64 v[214:215], s[40:41], 0, v[138:139]
	s_add_i32 m0, s29, 0xe000
	s_nop 0
	global_load_lds_dwordx4 v[214:215], off
	s_waitcnt vmcnt(8)
	s_waitcnt lgkmcnt(0)
	s_barrier
	s_setprio 1
	s_waitcnt lgkmcnt(0)
	v_mfma_f32_16x16x32_bf16 v[124:127], v[150:153], v[182:185], 0
	v_mfma_f32_16x16x32_bf16 v[120:123], v[158:161], v[182:185], 0
	v_mfma_f32_16x16x32_bf16 v[116:119], v[150:153], v[190:193], 0
	v_mfma_f32_16x16x32_bf16 v[112:115], v[158:161], v[190:193], 0
	v_mfma_f32_16x16x32_bf16 v[100:103], v[150:153], v[198:201], 0
	v_mfma_f32_16x16x32_bf16 v[96:99], v[158:161], v[198:201], 0
	v_mfma_f32_16x16x32_bf16 v[84:87], v[150:153], v[206:209], 0
	v_mfma_f32_16x16x32_bf16 v[80:83], v[158:161], v[206:209], 0
	v_mfma_f32_16x16x32_bf16 v[124:127], v[154:157], v[186:189], v[124:127]
	v_mfma_f32_16x16x32_bf16 v[120:123], v[162:165], v[186:189], v[120:123]
	v_mfma_f32_16x16x32_bf16 v[116:119], v[154:157], v[194:197], v[116:119]
	v_mfma_f32_16x16x32_bf16 v[112:115], v[162:165], v[194:197], v[112:115]
	v_mfma_f32_16x16x32_bf16 v[100:103], v[154:157], v[202:205], v[100:103]
	v_mfma_f32_16x16x32_bf16 v[96:99], v[162:165], v[202:205], v[96:99]
	v_mfma_f32_16x16x32_bf16 v[84:87], v[154:157], v[210:213], v[84:87]
	v_mfma_f32_16x16x32_bf16 v[80:83], v[162:165], v[210:213], v[80:83]
	s_setprio 0
	s_setprio 1
	v_mfma_f32_16x16x32_bf16 v[108:111], v[166:169], v[182:185], 0
	v_mfma_f32_16x16x32_bf16 v[104:107], v[174:177], v[182:185], 0
	v_mfma_f32_16x16x32_bf16 v[92:95], v[166:169], v[190:193], 0
	v_mfma_f32_16x16x32_bf16 v[88:91], v[174:177], v[190:193], 0
	v_mfma_f32_16x16x32_bf16 v[76:79], v[166:169], v[198:201], 0
	v_mfma_f32_16x16x32_bf16 v[72:75], v[174:177], v[198:201], 0
	v_mfma_f32_16x16x32_bf16 v[68:71], v[166:169], v[206:209], 0
	v_mfma_f32_16x16x32_bf16 v[64:67], v[174:177], v[206:209], 0
	v_mfma_f32_16x16x32_bf16 v[108:111], v[170:173], v[186:189], v[108:111]
	v_mfma_f32_16x16x32_bf16 v[104:107], v[178:181], v[186:189], v[104:107]
	v_mfma_f32_16x16x32_bf16 v[92:95], v[170:173], v[194:197], v[92:95]
	v_mfma_f32_16x16x32_bf16 v[88:91], v[178:181], v[194:197], v[88:91]
	v_mfma_f32_16x16x32_bf16 v[76:79], v[170:173], v[202:205], v[76:79]
	v_mfma_f32_16x16x32_bf16 v[72:75], v[178:181], v[202:205], v[72:75]
	v_mfma_f32_16x16x32_bf16 v[68:71], v[170:173], v[210:213], v[68:71]
	v_mfma_f32_16x16x32_bf16 v[64:67], v[178:181], v[210:213], v[64:67]
	s_setprio 0
	s_barrier
	s_add_i32 s7, s58, s50
	v_lshl_add_u64 v[214:215], s[42:43], 0, v[130:131]
	s_mov_b32 m0, s7
	ds_read_b128 v[182:185], v149 offset:16384
	ds_read_b128 v[186:189], v149 offset:17408
	ds_read_b128 v[190:193], v149 offset:18432
	ds_read_b128 v[194:197], v149 offset:19456
	ds_read_b128 v[198:201], v149 offset:20480
	ds_read_b128 v[202:205], v149 offset:21504
	ds_read_b128 v[206:209], v149 offset:22528
	ds_read_b128 v[210:213], v149 offset:23552
	global_load_lds_dwordx4 v[214:215], off
	s_add_i32 m0, s7, 0x2000
	s_add_u32 s70, s42, 0x80000
	v_lshl_add_u64 v[218:219], s[42:43], 0, v[134:135]
	s_addc_u32 s71, s43, 0
	s_add_i32 s7, s59, s50
	global_load_lds_dwordx4 v[218:219], off
	v_lshl_add_u64 v[220:221], s[70:71], 0, v[130:131]
	s_mov_b32 m0, s7
	v_lshl_add_u64 v[222:223], s[44:45], 0, v[132:133]
	global_load_lds_dwordx4 v[220:221], off
	v_lshl_add_u64 v[220:221], s[70:71], 0, v[134:135]
	s_add_i32 m0, s7, 0x2000
	s_nop 0
	global_load_lds_dwordx4 v[220:221], off
	v_lshl_add_u64 v[220:221], s[44:45], 0, v[128:129]
	s_mov_b32 m0, s29
	s_nop 0
	global_load_lds_dwordx4 v[220:221], off
	s_mov_b32 m0, s51
	s_nop 0
	global_load_lds_dwordx4 v[222:223], off
	s_waitcnt vmcnt(8)
	s_waitcnt lgkmcnt(0)
	s_barrier
; #define PG8_STAGE(bufoff, gbase, voff) do { _Pragma("unroll") for (int _i = 0; _i < 2; ++_i) \
;         __builtin_amdgcn_global_load_lds((const unsigned*)((const char*)(gbase) + (voff)[_i]), (LAS unsigned*)(lds + (bufoff) + ldsw + _i * 8192), 16, 0, 0); } while (0)
; #define PG8_LDA(dst, b, h) do { _Pragma("unroll") for (int m = 0; m < 4; ++m) _Pragma("unroll") for (int k = 0; k < 2; ++k) dst[m][k] = *(const LAS bf16x8*)(lds + PG8_SA(b, h) + aoff + m * 2048 + k * 1024); } while (0)
; #define PG8_LDB(dst, b, h) do { _Pragma("unroll") for (int n = 0; n < 2; ++n) _Pragma("unroll") for (int k = 0; k < 2; ++k) dst[n][k] = *(const LAS bf16x8*)(lds + PG8_SB(b, h) + boff + n * 2048 + k * 1024); } while (0)
; #define PG8_WAIT_V(n) asm volatile("s_waitcnt vmcnt(" #n ")" ::: "memory")
; #define PG8_WAIT_L(n) asm volatile("s_waitcnt lgkmcnt(" #n ")" ::: "memory")
; #define PG8_BAR __builtin_amdgcn_s_barrier()
; #define PG8_SCHED __builtin_amdgcn_sched_barrier(0)
; template <class Epi, class Sched, bool ALIGN_EPI, bool I8 = false>
; __device__ __forceinline__ void gemm_phase(LAS unsigned char* lds, const Gemm g, const Sched& S, const Epi& E) {
;     ...
;             PG8_WAIT_V(8); PG8_WAIT_L(0); PG8_BAR; PG8_MMA(1, 0, At, B0); PG8_MMA(1, 1, At, B1); PG8_BAR; PG8_SCHED;
;             PG8_LDB(B0, 1, 0); PG8_LDB(B1, 1, 1); PG8_SCHED; PG8_LDA(At, 1, 0); PG8_STAGE(PG8_SA(0, 1), a2 + hstep, voffA);
;             PG8_WAIT_V(8); PG8_WAIT_L(0); PG8_BAR; PG8_MMA(0, 0, At, B0); PG8_MMA(0, 1, At, B1); PG8_BAR; PG8_SCHED;
	s_setprio 1
	s_waitcnt lgkmcnt(0)
	v_mfma_f32_16x16x32_bf16 v[60:63], v[150:153], v[182:185], 0
	v_mfma_f32_16x16x32_bf16 v[56:59], v[158:161], v[182:185], 0
	v_mfma_f32_16x16x32_bf16 v[52:55], v[150:153], v[190:193], 0
	v_mfma_f32_16x16x32_bf16 v[48:51], v[158:161], v[190:193], 0
	v_mfma_f32_16x16x32_bf16 v[36:39], v[150:153], v[198:201], 0
	v_mfma_f32_16x16x32_bf16 v[32:35], v[158:161], v[198:201], 0
	v_mfma_f32_16x16x32_bf16 v[20:23], v[150:153], v[206:209], 0
	v_mfma_f32_16x16x32_bf16 v[16:19], v[158:161], v[206:209], 0
	v_mfma_f32_16x16x32_bf16 v[60:63], v[154:157], v[186:189], v[60:63]
	v_mfma_f32_16x16x32_bf16 v[56:59], v[162:165], v[186:189], v[56:59]
	v_mfma_f32_16x16x32_bf16 v[52:55], v[154:157], v[194:197], v[52:55]
	v_mfma_f32_16x16x32_bf16 v[48:51], v[162:165], v[194:197], v[48:51]
	v_mfma_f32_16x16x32_bf16 v[36:39], v[154:157], v[202:205], v[36:39]
	v_mfma_f32_16x16x32_bf16 v[32:35], v[162:165], v[202:205], v[32:35]
	v_mfma_f32_16x16x32_bf16 v[20:23], v[154:157], v[210:213], v[20:23]
	v_mfma_f32_16x16x32_bf16 v[16:19], v[162:165], v[210:213], v[16:19]
	s_setprio 0
	s_setprio 1
	v_mfma_f32_16x16x32_bf16 v[44:47], v[166:169], v[182:185], 0
	v_mfma_f32_16x16x32_bf16 v[40:43], v[174:177], v[182:185], 0
	v_mfma_f32_16x16x32_bf16 v[28:31], v[166:169], v[190:193], 0
	v_mfma_f32_16x16x32_bf16 v[24:27], v[174:177], v[190:193], 0
	v_mfma_f32_16x16x32_bf16 v[12:15], v[166:169], v[198:201], 0
	v_mfma_f32_16x16x32_bf16 v[8:11], v[174:177], v[198:201], 0
	v_mfma_f32_16x16x32_bf16 v[4:7], v[166:169], v[206:209], 0
	v_mfma_f32_16x16x32_bf16 v[0:3], v[174:177], v[206:209], 0
	v_mfma_f32_16x16x32_bf16 v[44:47], v[170:173], v[186:189], v[44:47]
	v_mfma_f32_16x16x32_bf16 v[40:43], v[178:181], v[186:189], v[40:43]
	v_mfma_f32_16x16x32_bf16 v[28:31], v[170:173], v[194:197], v[28:31]
	v_mfma_f32_16x16x32_bf16 v[24:27], v[178:181], v[194:197], v[24:27]
	v_mfma_f32_16x16x32_bf16 v[12:15], v[170:173], v[202:205], v[12:15]
	v_mfma_f32_16x16x32_bf16 v[8:11], v[178:181], v[202:205], v[8:11]
	v_mfma_f32_16x16x32_bf16 v[4:7], v[170:173], v[210:213], v[4:7]
	v_mfma_f32_16x16x32_bf16 v[0:3], v[178:181], v[210:213], v[0:3]
	s_setprio 0
	s_barrier
	s_add_i32 s7, 0, 0x18000
	s_add_i32 s70, 0, 0x1c000
	v_add_u32_e32 v162, s7, v145
	v_add_u32_e32 v178, s70, v145
	ds_read_b128 v[150:153], v162
	ds_read_b128 v[154:157], v162 offset:1024
	ds_read_b128 v[158:161], v162 offset:2048
	ds_read_b128 v[162:165], v162 offset:3072
	ds_read_b128 v[166:169], v178
	ds_read_b128 v[170:173], v178 offset:1024
	ds_read_b128 v[174:177], v178 offset:2048
	ds_read_b128 v[178:181], v178 offset:3072
	s_add_u32 s44, s44, 0x80000
	s_addc_u32 s45, s45, 0
	s_mov_b32 m0, s52
	v_lshl_add_u64 v[224:225], s[44:45], 0, v[128:129]
	ds_read_b128 v[182:185], v149 offset:32768
	ds_read_b128 v[186:189], v149 offset:33792
	ds_read_b128 v[190:193], v149 offset:34816
	ds_read_b128 v[194:197], v149 offset:35840
	ds_read_b128 v[198:201], v149 offset:36864
	ds_read_b128 v[202:205], v149 offset:37888
	ds_read_b128 v[206:209], v149 offset:38912
	ds_read_b128 v[210:213], v149 offset:39936
	global_load_lds_dwordx4 v[224:225], off
	v_lshl_add_u64 v[224:225], s[44:45], 0, v[132:133]
	s_mov_b32 m0, s53
	s_nop 0
	global_load_lds_dwordx4 v[224:225], off
	s_waitcnt vmcnt(8)
	s_waitcnt lgkmcnt(0)
	s_barrier
	s_setprio 1
	s_waitcnt lgkmcnt(0)
	v_mfma_f32_16x16x32_bf16 v[124:127], v[150:153], v[182:185], v[124:127]
	v_mfma_f32_16x16x32_bf16 v[120:123], v[158:161], v[182:185], v[120:123]
	v_mfma_f32_16x16x32_bf16 v[116:119], v[150:153], v[190:193], v[116:119]
	v_mfma_f32_16x16x32_bf16 v[112:115], v[158:161], v[190:193], v[112:115]
	v_mfma_f32_16x16x32_bf16 v[100:103], v[150:153], v[198:201], v[100:103]
	v_mfma_f32_16x16x32_bf16 v[96:99], v[158:161], v[198:201], v[96:99]
	v_mfma_f32_16x16x32_bf16 v[84:87], v[150:153], v[206:209], v[84:87]
	v_mfma_f32_16x16x32_bf16 v[80:83], v[158:161], v[206:209], v[80:83]
	v_mfma_f32_16x16x32_bf16 v[124:127], v[154:157], v[186:189], v[124:127]
	v_mfma_f32_16x16x32_bf16 v[120:123], v[162:165], v[186:189], v[120:123]
	v_mfma_f32_16x16x32_bf16 v[116:119], v[154:157], v[194:197], v[116:119]
	v_mfma_f32_16x16x32_bf16 v[112:115], v[162:165], v[194:197], v[112:115]
	v_mfma_f32_16x16x32_bf16 v[100:103], v[154:157], v[202:205], v[100:103]
	v_mfma_f32_16x16x32_bf16 v[96:99], v[162:165], v[202:205], v[96:99]
	v_mfma_f32_16x16x32_bf16 v[84:87], v[154:157], v[210:213], v[84:87]
	v_mfma_f32_16x16x32_bf16 v[80:83], v[162:165], v[210:213], v[80:83]
	s_setprio 0
	s_setprio 1
	v_mfma_f32_16x16x32_bf16 v[108:111], v[166:169], v[182:185], v[108:111]
	v_mfma_f32_16x16x32_bf16 v[104:107], v[174:177], v[182:185], v[104:107]
	v_mfma_f32_16x16x32_bf16 v[92:95], v[166:169], v[190:193], v[92:95]
	v_mfma_f32_16x16x32_bf16 v[88:91], v[174:177], v[190:193], v[88:91]
	v_mfma_f32_16x16x32_bf16 v[76:79], v[166:169], v[198:201], v[76:79]
	v_mfma_f32_16x16x32_bf16 v[72:75], v[174:177], v[198:201], v[72:75]
	v_mfma_f32_16x16x32_bf16 v[68:71], v[166:169], v[206:209], v[68:71]
	v_mfma_f32_16x16x32_bf16 v[64:67], v[174:177], v[206:209], v[64:67]
	v_mfma_f32_16x16x32_bf16 v[108:111], v[170:173], v[186:189], v[108:111]
	v_mfma_f32_16x16x32_bf16 v[104:107], v[178:181], v[186:189], v[104:107]
	v_mfma_f32_16x16x32_bf16 v[92:95], v[170:173], v[194:197], v[92:95]
	v_mfma_f32_16x16x32_bf16 v[88:91], v[178:181], v[194:197], v[88:91]
	v_mfma_f32_16x16x32_bf16 v[76:79], v[170:173], v[202:205], v[76:79]
	v_mfma_f32_16x16x32_bf16 v[72:75], v[178:181], v[202:205], v[72:75]
	v_mfma_f32_16x16x32_bf16 v[68:71], v[170:173], v[210:213], v[68:71]
	v_mfma_f32_16x16x32_bf16 v[64:67], v[178:181], v[210:213], v[64:67]
	s_setprio 0
	s_barrier
; #define PG8_STAGE(bufoff, gbase, voff) do { _Pragma("unroll") for (int _i = 0; _i < 2; ++_i) \
;         __builtin_amdgcn_global_load_lds((const unsigned*)((const char*)(gbase) + (voff)[_i]), (LAS unsigned*)(lds + (bufoff) + ldsw + _i * 8192), 16, 0, 0); } while (0)
; #define PG8_LDA(dst, b, h) do { _Pragma("unroll") for (int m = 0; m < 4; ++m) _Pragma("unroll") for (int k = 0; k < 2; ++k) dst[m][k] = *(const LAS bf16x8*)(lds + PG8_SA(b, h) + aoff + m * 2048 + k * 1024); } while (0)
; #define PG8_WAIT_V(n) asm volatile("s_waitcnt vmcnt(" #n ")" ::: "memory")
; #define PG8_WAIT_L(n) asm volatile("s_waitcnt lgkmcnt(" #n ")" ::: "memory")
; #define PG8_BAR __builtin_amdgcn_s_barrier()
; #define PG8_SCHED __builtin_amdgcn_sched_barrier(0)
; template <class Epi, class Sched, bool ALIGN_EPI, bool I8 = false>
; __device__ __forceinline__ void gemm_phase(LAS unsigned char* lds, const Gemm g, const Sched& S, const Epi& E) {
;     ...
;             PG8_LDA(At, 1, 1); PG8_STAGE(PG8_SB(1, 0), b3, voffB); PG8_STAGE(PG8_SB(1, 1), b3 + hstep, voffB); PG8_STAGE(PG8_SA(1, 0), a3, voffA);
;             PG8_WAIT_V(8); PG8_WAIT_L(0); PG8_BAR; PG8_MMA(1, 0, At, B0); PG8_MMA(1, 1, At, B1); PG8_BAR; PG8_SCHED;
;         }
	s_add_i32 s7, s7, s50
	v_lshl_add_u64 v[214:215], v[214:215], 0, s[14:15]
	s_mov_b32 m0, s7
	ds_read_b128 v[182:185], v149 offset:49152
	ds_read_b128 v[186:189], v149 offset:50176
	ds_read_b128 v[190:193], v149 offset:51200
	ds_read_b128 v[194:197], v149 offset:52224
	ds_read_b128 v[198:201], v149 offset:53248
	ds_read_b128 v[202:205], v149 offset:54272
	ds_read_b128 v[206:209], v149 offset:55296
	ds_read_b128 v[210:213], v149 offset:56320
	global_load_lds_dwordx4 v[214:215], off
	s_add_i32 m0, s7, 0x2000
	s_add_u32 s42, s42, 0x80080
	v_lshl_add_u64 v[214:215], v[218:219], 0, s[14:15]
	s_addc_u32 s43, s43, 0
	s_add_i32 s7, s70, s50
	global_load_lds_dwordx4 v[214:215], off
	v_lshl_add_u64 v[214:215], s[42:43], 0, v[130:131]
	s_mov_b32 m0, s7
	s_nop 0
	global_load_lds_dwordx4 v[214:215], off
	v_lshl_add_u64 v[214:215], s[42:43], 0, v[134:135]
	s_add_i32 m0, s7, 0x2000
	s_nop 0
	global_load_lds_dwordx4 v[214:215], off
	v_lshl_add_u64 v[214:215], v[220:221], 0, s[14:15]
	s_mov_b32 m0, s55
	s_nop 0
	global_load_lds_dwordx4 v[214:215], off
	v_lshl_add_u64 v[214:215], v[222:223], 0, s[14:15]
	s_mov_b32 m0, s56
	s_nop 0
	global_load_lds_dwordx4 v[214:215], off
	s_waitcnt vmcnt(8)
	s_waitcnt lgkmcnt(0)
	s_barrier
	s_setprio 1
	s_waitcnt lgkmcnt(0)
	v_mfma_f32_16x16x32_bf16 v[60:63], v[150:153], v[182:185], v[60:63]
	v_mfma_f32_16x16x32_bf16 v[56:59], v[158:161], v[182:185], v[56:59]
	v_mfma_f32_16x16x32_bf16 v[52:55], v[150:153], v[190:193], v[52:55]
	v_mfma_f32_16x16x32_bf16 v[48:51], v[158:161], v[190:193], v[48:51]
	v_mfma_f32_16x16x32_bf16 v[36:39], v[150:153], v[198:201], v[36:39]
	v_mfma_f32_16x16x32_bf16 v[32:35], v[158:161], v[198:201], v[32:35]
	v_mfma_f32_16x16x32_bf16 v[20:23], v[150:153], v[206:209], v[20:23]
	v_mfma_f32_16x16x32_bf16 v[16:19], v[158:161], v[206:209], v[16:19]
	v_mfma_f32_16x16x32_bf16 v[60:63], v[154:157], v[186:189], v[60:63]
	v_mfma_f32_16x16x32_bf16 v[56:59], v[162:165], v[186:189], v[56:59]
	v_mfma_f32_16x16x32_bf16 v[52:55], v[154:157], v[194:197], v[52:55]
	v_mfma_f32_16x16x32_bf16 v[48:51], v[162:165], v[194:197], v[48:51]
	v_mfma_f32_16x16x32_bf16 v[36:39], v[154:157], v[202:205], v[36:39]
	v_mfma_f32_16x16x32_bf16 v[32:35], v[162:165], v[202:205], v[32:35]
	v_mfma_f32_16x16x32_bf16 v[20:23], v[154:157], v[210:213], v[20:23]
	v_mfma_f32_16x16x32_bf16 v[16:19], v[162:165], v[210:213], v[16:19]
	s_setprio 0
	s_setprio 1
	v_mfma_f32_16x16x32_bf16 v[44:47], v[166:169], v[182:185], v[44:47]
	v_mfma_f32_16x16x32_bf16 v[40:43], v[174:177], v[182:185], v[40:43]
	v_mfma_f32_16x16x32_bf16 v[28:31], v[166:169], v[190:193], v[28:31]
	v_mfma_f32_16x16x32_bf16 v[24:27], v[174:177], v[190:193], v[24:27]
	v_mfma_f32_16x16x32_bf16 v[12:15], v[166:169], v[198:201], v[12:15]
	v_mfma_f32_16x16x32_bf16 v[8:11], v[174:177], v[198:201], v[8:11]
	v_mfma_f32_16x16x32_bf16 v[4:7], v[166:169], v[206:209], v[4:7]
	v_mfma_f32_16x16x32_bf16 v[0:3], v[174:177], v[206:209], v[0:3]
	v_mfma_f32_16x16x32_bf16 v[44:47], v[170:173], v[186:189], v[44:47]
	v_mfma_f32_16x16x32_bf16 v[40:43], v[178:181], v[186:189], v[40:43]
	v_mfma_f32_16x16x32_bf16 v[28:31], v[170:173], v[194:197], v[28:31]
	v_mfma_f32_16x16x32_bf16 v[24:27], v[178:181], v[194:197], v[24:27]
	v_mfma_f32_16x16x32_bf16 v[12:15], v[170:173], v[202:205], v[12:15]
	v_mfma_f32_16x16x32_bf16 v[8:11], v[178:181], v[202:205], v[8:11]
	v_mfma_f32_16x16x32_bf16 v[4:7], v[170:173], v[210:213], v[4:7]
	v_mfma_f32_16x16x32_bf16 v[0:3], v[178:181], v[210:213], v[0:3]
	s_setprio 0
	s_barrier
	s_add_i32 s69, s69, 2
	s_add_u32 s40, s40, 0x100
	s_addc_u32 s41, s41, 0
	s_add_u32 s67, s67, 0x100
	s_addc_u32 s68, s68, 0
	s_cmp_gt_u32 s69, 29
	s_cbranch_scc1 .Lpeel_exit_18350

; #define PG8_BAR __builtin_amdgcn_s_barrier()
; template <class Epi, class Sched, bool ALIGN_EPI, bool I8 = false>
; __device__ __forceinline__ void gemm_phase(LAS unsigned char* lds, const Gemm g, const Sched& S, const Epi& E) {
;     ...
;         if constexpr (ALIGN_EPI) { if (wr == 0) PG8_BAR; }
.Lpeel_exit_18350:
	s_and_b64 vcc, exec, s[16:17]
	s_cbranch_vccz .LBB0_415
	s_barrier

; #define PG8_STAGE(bufoff, gbase, voff) do { _Pragma("unroll") for (int _i = 0; _i < 2; ++_i) \
;         __builtin_amdgcn_global_load_lds((const unsigned*)((const char*)(gbase) + (voff)[_i]), (LAS unsigned*)(lds + (bufoff) + ldsw + _i * 8192), 16, 0, 0); } while (0)
; #define PG8_LDA(dst, b, h) do { _Pragma("unroll") for (int m = 0; m < 4; ++m) _Pragma("unroll") for (int k = 0; k < 2; ++k) dst[m][k] = *(const LAS bf16x8*)(lds + PG8_SA(b, h) + aoff + m * 2048 + k * 1024); } while (0)
; #define PG8_BAR __builtin_amdgcn_s_barrier()
; template <class Epi, class Sched, bool ALIGN_EPI, bool I8 = false>
; __device__ __forceinline__ void gemm_phase(LAS unsigned char* lds, const Gemm g, const Sched& S, const Epi& E) {
;     ...
;         const bool has_next = S.next(ui + 1, nxt);
;         const char* nA = has_next ? (const char*)g.A + (size_t)nxt.z * g.zA + (size_t)nxt.pm * tstep : cA;
;         const char* nB = has_next ? (const char*)g.Bt + (size_t)nxt.z * g.zB + (size_t)nxt.pn * tstep : cB;
;         for (int t = 0; t < nt; t += 2) {
;             const bool last = (t == nt - 2);
;             const char* a1 = cA + (size_t)(t + 1) * kstep;
;             const char* a2 = last ? nA : cA + (size_t)(t + 2) * kstep; const char* b2 = last ? nB : cB + (size_t)(t + 2) * kstep;
;             const char* a3 = a2 + kstep; const char* b3 = b2 + kstep;
;             PG8_LDB(B0, 0, 0); PG8_LDB(B1, 0, 1); PG8_SCHED; PG8_LDA(At, 0, 0); PG8_STAGE(PG8_SA(1, 1), a1 + hstep, voffA);
;             PG8_WAIT_V(8); PG8_WAIT_L(0); PG8_BAR; PG8_MMA(0, 0, At, B0); PG8_MMA(0, 1, At, B1); PG8_BAR; PG8_SCHED;
;             PG8_LDA(At, 0, 1); PG8_STAGE(PG8_SB(0, 0), b2, voffB); PG8_STAGE(PG8_SB(0, 1), b2 + hstep, voffB); PG8_STAGE(PG8_SA(0, 0), a2, voffA);
;             PG8_WAIT_V(8); PG8_WAIT_L(0); PG8_BAR; PG8_MMA(1, 0, At, B0); PG8_MMA(1, 1, At, B1); PG8_BAR; PG8_SCHED;
;             PG8_LDB(B0, 1, 0); PG8_LDB(B1, 1, 1); PG8_SCHED; PG8_LDA(At, 1, 0); PG8_STAGE(PG8_SA(0, 1), a2 + hstep, voffA);
;             PG8_WAIT_V(8); PG8_WAIT_L(0); PG8_BAR; PG8_MMA(0, 0, At, B0); PG8_MMA(0, 1, At, B1); PG8_BAR; PG8_SCHED;
;             PG8_LDA(At, 1, 1); PG8_STAGE(PG8_SB(1, 0), b3, voffB); PG8_STAGE(PG8_SB(1, 1), b3 + hstep, voffB); PG8_STAGE(PG8_SA(1, 0), a3, voffA);
;             PG8_WAIT_V(8); PG8_WAIT_L(0); PG8_BAR; PG8_MMA(1, 0, At, B0); PG8_MMA(1, 1, At, B1); PG8_BAR; PG8_SCHED;
.LBB0_566:
	s_ashr_i32 s47, s46, 31
	s_lshl_b64 s[48:49], s[46:47], 19
	s_add_u32 s48, s27, s48
	s_addc_u32 s49, s39, s49
	s_and_b64 s[50:51], s[2:3], exec
	s_cselect_b32 s47, s49, s53
	s_cselect_b32 s55, s48, s52
	s_ashr_i32 s45, s44, 31
	s_lshl_b64 s[50:51], s[44:45], 19
	s_add_u32 s50, s41, s50
	s_addc_u32 s51, s43, s51
	s_and_b64 s[58:59], s[2:3], exec
	s_cselect_b32 s45, s51, s57
	s_cselect_b32 s61, s50, s56
	s_add_u32 s52, s52, 0x40080
	s_addc_u32 s53, s53, 0
	s_add_u32 s62, s56, 0x100
	s_addc_u32 s63, s57, 0
	s_mov_b32 vcc_lo, -2
	ds_read_b128 v[128:131], v225
	ds_read_b128 v[132:135], v225 offset:1024
	ds_read_b128 v[136:139], v225 offset:2048
	ds_read_b128 v[140:143], v225 offset:3072
	ds_read_b128 v[164:167], v226
	ds_read_b128 v[168:171], v226 offset:1024
	ds_read_b128 v[172:175], v226 offset:2048
	ds_read_b128 v[176:179], v226 offset:3072
	s_add_u32 s4, s52, 0xfffc0080
	s_addc_u32 s5, s53, -1
	s_cmp_eq_u32 vcc_lo, 12
	s_cselect_b32 s59, s47, s5
	s_cselect_b32 s58, s55, s4
	s_cselect_b32 s57, s45, s63
	s_cselect_b32 s56, s61, s62
	v_lshl_add_u64 v[212:213], s[52:53], 0, v[156:157]
	s_add_i32 m0, s67, 0xc000
	ds_read_b128 v[180:183], v227
	ds_read_b128 v[184:187], v227 offset:1024
	ds_read_b128 v[188:191], v227 offset:2048
	ds_read_b128 v[192:195], v227 offset:3072
	ds_read_b128 v[196:199], v227 offset:4096
	ds_read_b128 v[200:203], v227 offset:5120
	ds_read_b128 v[204:207], v227 offset:6144
	ds_read_b128 v[208:211], v227 offset:7168
	global_load_lds_dwordx4 v[212:213], off
	v_lshl_add_u64 v[212:213], s[52:53], 0, v[158:159]
	s_add_i32 m0, s67, 0xe000
	s_nop 0
	global_load_lds_dwordx4 v[212:213], off
	s_waitcnt vmcnt(8)
	s_waitcnt lgkmcnt(0)
	s_barrier
	s_setprio 1
	s_waitcnt lgkmcnt(0)
	v_mfma_i32_16x16x64_i8 v[124:127], v[128:131], v[180:183], 0
	v_mfma_i32_16x16x64_i8 v[120:123], v[136:139], v[180:183], 0
	v_mfma_i32_16x16x64_i8 v[108:111], v[128:131], v[188:191], 0
	v_mfma_i32_16x16x64_i8 v[104:107], v[136:139], v[188:191], 0
	v_mfma_i32_16x16x64_i8 v[92:95], v[128:131], v[196:199], 0
	v_mfma_i32_16x16x64_i8 v[88:91], v[136:139], v[196:199], 0
	v_mfma_i32_16x16x64_i8 v[76:79], v[128:131], v[204:207], 0
	v_mfma_i32_16x16x64_i8 v[72:75], v[136:139], v[204:207], 0
	v_mfma_i32_16x16x64_i8 v[124:127], v[132:135], v[184:187], v[124:127]
	v_mfma_i32_16x16x64_i8 v[120:123], v[140:143], v[184:187], v[120:123]
	v_mfma_i32_16x16x64_i8 v[108:111], v[132:135], v[192:195], v[108:111]
	v_mfma_i32_16x16x64_i8 v[104:107], v[140:143], v[192:195], v[104:107]
	v_mfma_i32_16x16x64_i8 v[92:95], v[132:135], v[200:203], v[92:95]
	v_mfma_i32_16x16x64_i8 v[88:91], v[140:143], v[200:203], v[88:91]
	v_mfma_i32_16x16x64_i8 v[76:79], v[132:135], v[208:211], v[76:79]
	v_mfma_i32_16x16x64_i8 v[72:75], v[140:143], v[208:211], v[72:75]
	s_setprio 0
	s_setprio 1
	v_mfma_i32_16x16x64_i8 v[116:119], v[164:167], v[180:183], 0
	v_mfma_i32_16x16x64_i8 v[112:115], v[172:175], v[180:183], 0
	v_mfma_i32_16x16x64_i8 v[100:103], v[164:167], v[188:191], 0
	v_mfma_i32_16x16x64_i8 v[96:99], v[172:175], v[188:191], 0
	v_mfma_i32_16x16x64_i8 v[84:87], v[164:167], v[196:199], 0
	v_mfma_i32_16x16x64_i8 v[80:83], v[172:175], v[196:199], 0
	v_mfma_i32_16x16x64_i8 v[68:71], v[164:167], v[204:207], 0
	v_mfma_i32_16x16x64_i8 v[64:67], v[172:175], v[204:207], 0
	v_mfma_i32_16x16x64_i8 v[116:119], v[168:171], v[184:187], v[116:119]
	v_mfma_i32_16x16x64_i8 v[112:115], v[176:179], v[184:187], v[112:115]
	v_mfma_i32_16x16x64_i8 v[100:103], v[168:171], v[192:195], v[100:103]
	v_mfma_i32_16x16x64_i8 v[96:99], v[176:179], v[192:195], v[96:99]
	v_mfma_i32_16x16x64_i8 v[84:87], v[168:171], v[200:203], v[84:87]
	v_mfma_i32_16x16x64_i8 v[80:83], v[176:179], v[200:203], v[80:83]
	v_mfma_i32_16x16x64_i8 v[68:71], v[168:171], v[208:211], v[68:71]
	v_mfma_i32_16x16x64_i8 v[64:67], v[176:179], v[208:211], v[64:67]
	s_setprio 0
	s_barrier
	s_add_i32 s4, s79, s64
	v_lshl_add_u64 v[212:213], s[56:57], 0, v[148:149]
	s_mov_b32 m0, s4
	ds_read_b128 v[180:183], v227 offset:16384
	ds_read_b128 v[184:187], v227 offset:17408
	ds_read_b128 v[188:191], v227 offset:18432
	ds_read_b128 v[192:195], v227 offset:19456
	ds_read_b128 v[196:199], v227 offset:20480
	ds_read_b128 v[200:203], v227 offset:21504
	ds_read_b128 v[204:207], v227 offset:22528
	ds_read_b128 v[208:211], v227 offset:23552
	global_load_lds_dwordx4 v[212:213], off
	s_add_i32 m0, s4, 0x2000
	s_add_u32 s4, s56, 0x40000
	v_lshl_add_u64 v[214:215], s[56:57], 0, v[144:145]
	s_addc_u32 s5, s57, 0
	s_add_i32 s7, s80, s64
	global_load_lds_dwordx4 v[214:215], off
	v_lshl_add_u64 v[220:221], s[4:5], 0, v[148:149]
	s_mov_b32 m0, s7
	v_lshl_add_u64 v[228:229], s[58:59], 0, v[146:147]
	global_load_lds_dwordx4 v[220:221], off
	v_lshl_add_u64 v[220:221], s[4:5], 0, v[144:145]
	s_add_i32 m0, s7, 0x2000
	s_nop 0
	global_load_lds_dwordx4 v[220:221], off
	v_lshl_add_u64 v[220:221], s[58:59], 0, v[150:151]
	s_mov_b32 m0, s67
	s_nop 0
	global_load_lds_dwordx4 v[220:221], off
	s_mov_b32 m0, s68
	s_nop 0
	global_load_lds_dwordx4 v[228:229], off
	s_waitcnt vmcnt(8)
	s_waitcnt lgkmcnt(0)
	s_barrier
; #define PG8_STAGE(bufoff, gbase, voff) do { _Pragma("unroll") for (int _i = 0; _i < 2; ++_i) \
;         __builtin_amdgcn_global_load_lds((const unsigned*)((const char*)(gbase) + (voff)[_i]), (LAS unsigned*)(lds + (bufoff) + ldsw + _i * 8192), 16, 0, 0); } while (0)
; #define PG8_LDA(dst, b, h) do { _Pragma("unroll") for (int m = 0; m < 4; ++m) _Pragma("unroll") for (int k = 0; k < 2; ++k) dst[m][k] = *(const LAS bf16x8*)(lds + PG8_SA(b, h) + aoff + m * 2048 + k * 1024); } while (0)
; #define PG8_LDB(dst, b, h) do { _Pragma("unroll") for (int n = 0; n < 2; ++n) _Pragma("unroll") for (int k = 0; k < 2; ++k) dst[n][k] = *(const LAS bf16x8*)(lds + PG8_SB(b, h) + boff + n * 2048 + k * 1024); } while (0)
; #define PG8_WAIT_V(n) asm volatile("s_waitcnt vmcnt(" #n ")" ::: "memory")
; #define PG8_WAIT_L(n) asm volatile("s_waitcnt lgkmcnt(" #n ")" ::: "memory")
; #define PG8_BAR __builtin_amdgcn_s_barrier()
; #define PG8_SCHED __builtin_amdgcn_sched_barrier(0)
; template <class Epi, class Sched, bool ALIGN_EPI, bool I8 = false>
; __device__ __forceinline__ void gemm_phase(LAS unsigned char* lds, const Gemm g, const Sched& S, const Epi& E) {
;     ...
;             PG8_WAIT_V(8); PG8_WAIT_L(0); PG8_BAR; PG8_MMA(1, 0, At, B0); PG8_MMA(1, 1, At, B1); PG8_BAR; PG8_SCHED;
;             PG8_LDB(B0, 1, 0); PG8_LDB(B1, 1, 1); PG8_SCHED; PG8_LDA(At, 1, 0); PG8_STAGE(PG8_SA(0, 1), a2 + hstep, voffA);
;             PG8_WAIT_V(8); PG8_WAIT_L(0); PG8_BAR; PG8_MMA(0, 0, At, B0); PG8_MMA(0, 1, At, B1); PG8_BAR; PG8_SCHED;
	s_setprio 1
	s_waitcnt lgkmcnt(0)
	v_mfma_i32_16x16x64_i8 v[60:63], v[128:131], v[180:183], 0
	v_mfma_i32_16x16x64_i8 v[56:59], v[136:139], v[180:183], 0
	v_mfma_i32_16x16x64_i8 v[44:47], v[128:131], v[188:191], 0
	v_mfma_i32_16x16x64_i8 v[40:43], v[136:139], v[188:191], 0
	v_mfma_i32_16x16x64_i8 v[28:31], v[128:131], v[196:199], 0
	v_mfma_i32_16x16x64_i8 v[24:27], v[136:139], v[196:199], 0
	v_mfma_i32_16x16x64_i8 v[12:15], v[128:131], v[204:207], 0
	v_mfma_i32_16x16x64_i8 v[8:11], v[136:139], v[204:207], 0
	v_mfma_i32_16x16x64_i8 v[60:63], v[132:135], v[184:187], v[60:63]
	v_mfma_i32_16x16x64_i8 v[56:59], v[140:143], v[184:187], v[56:59]
	v_mfma_i32_16x16x64_i8 v[44:47], v[132:135], v[192:195], v[44:47]
	v_mfma_i32_16x16x64_i8 v[40:43], v[140:143], v[192:195], v[40:43]
	v_mfma_i32_16x16x64_i8 v[28:31], v[132:135], v[200:203], v[28:31]
	v_mfma_i32_16x16x64_i8 v[24:27], v[140:143], v[200:203], v[24:27]
	v_mfma_i32_16x16x64_i8 v[12:15], v[132:135], v[208:211], v[12:15]
	v_mfma_i32_16x16x64_i8 v[8:11], v[140:143], v[208:211], v[8:11]
	s_setprio 0
	s_setprio 1
	v_mfma_i32_16x16x64_i8 v[52:55], v[164:167], v[180:183], 0
	v_mfma_i32_16x16x64_i8 v[48:51], v[172:175], v[180:183], 0
	v_mfma_i32_16x16x64_i8 v[36:39], v[164:167], v[188:191], 0
	v_mfma_i32_16x16x64_i8 v[32:35], v[172:175], v[188:191], 0
	v_mfma_i32_16x16x64_i8 v[20:23], v[164:167], v[196:199], 0
	v_mfma_i32_16x16x64_i8 v[16:19], v[172:175], v[196:199], 0
	v_mfma_i32_16x16x64_i8 v[4:7], v[164:167], v[204:207], 0
	v_mfma_i32_16x16x64_i8 v[0:3], v[172:175], v[204:207], 0
	v_mfma_i32_16x16x64_i8 v[52:55], v[168:171], v[184:187], v[52:55]
	v_mfma_i32_16x16x64_i8 v[48:51], v[176:179], v[184:187], v[48:51]
	v_mfma_i32_16x16x64_i8 v[36:39], v[168:171], v[192:195], v[36:39]
	v_mfma_i32_16x16x64_i8 v[32:35], v[176:179], v[192:195], v[32:35]
	v_mfma_i32_16x16x64_i8 v[20:23], v[168:171], v[200:203], v[20:23]
	v_mfma_i32_16x16x64_i8 v[16:19], v[176:179], v[200:203], v[16:19]
	v_mfma_i32_16x16x64_i8 v[4:7], v[168:171], v[208:211], v[4:7]
	v_mfma_i32_16x16x64_i8 v[0:3], v[176:179], v[208:211], v[0:3]
	s_setprio 0
	s_barrier
	s_add_i32 s7, 0, 0x18000
	s_add_i32 vcc_hi, 0, 0x1c000
	v_add_u32_e32 v140, s7, v222
	v_add_u32_e32 v152, vcc_hi, v222
	ds_read_b128 v[128:131], v140
	ds_read_b128 v[132:135], v140 offset:1024
	ds_read_b128 v[136:139], v140 offset:2048
	ds_read_b128 v[140:143], v140 offset:3072
	ds_read_b128 v[164:167], v152
	ds_read_b128 v[168:171], v152 offset:1024
	ds_read_b128 v[172:175], v152 offset:2048
	ds_read_b128 v[176:179], v152 offset:3072
	s_add_u32 s4, s58, 0x40000
	s_addc_u32 s5, s59, 0
	s_mov_b32 m0, s69
	v_lshl_add_u64 v[230:231], s[4:5], 0, v[150:151]
	ds_read_b128 v[180:183], v227 offset:32768
	ds_read_b128 v[184:187], v227 offset:33792
	ds_read_b128 v[188:191], v227 offset:34816
	ds_read_b128 v[192:195], v227 offset:35840
	ds_read_b128 v[196:199], v227 offset:36864
	ds_read_b128 v[200:203], v227 offset:37888
	ds_read_b128 v[204:207], v227 offset:38912
	ds_read_b128 v[208:211], v227 offset:39936
	global_load_lds_dwordx4 v[230:231], off
	v_lshl_add_u64 v[230:231], s[4:5], 0, v[146:147]
	s_mov_b32 m0, s70
	s_nop 0
	global_load_lds_dwordx4 v[230:231], off
	s_waitcnt vmcnt(8)
	s_waitcnt lgkmcnt(0)
	s_barrier
	s_setprio 1
	s_waitcnt lgkmcnt(0)
	v_mfma_i32_16x16x64_i8 v[124:127], v[128:131], v[180:183], v[124:127]
	v_mfma_i32_16x16x64_i8 v[120:123], v[136:139], v[180:183], v[120:123]
	v_mfma_i32_16x16x64_i8 v[108:111], v[128:131], v[188:191], v[108:111]
	v_mfma_i32_16x16x64_i8 v[104:107], v[136:139], v[188:191], v[104:107]
	v_mfma_i32_16x16x64_i8 v[92:95], v[128:131], v[196:199], v[92:95]
	v_mfma_i32_16x16x64_i8 v[88:91], v[136:139], v[196:199], v[88:91]
	v_mfma_i32_16x16x64_i8 v[76:79], v[128:131], v[204:207], v[76:79]
	v_mfma_i32_16x16x64_i8 v[72:75], v[136:139], v[204:207], v[72:75]
	v_mfma_i32_16x16x64_i8 v[124:127], v[132:135], v[184:187], v[124:127]
	v_mfma_i32_16x16x64_i8 v[120:123], v[140:143], v[184:187], v[120:123]
	v_mfma_i32_16x16x64_i8 v[108:111], v[132:135], v[192:195], v[108:111]
	v_mfma_i32_16x16x64_i8 v[104:107], v[140:143], v[192:195], v[104:107]
	v_mfma_i32_16x16x64_i8 v[92:95], v[132:135], v[200:203], v[92:95]
	v_mfma_i32_16x16x64_i8 v[88:91], v[140:143], v[200:203], v[88:91]
	v_mfma_i32_16x16x64_i8 v[76:79], v[132:135], v[208:211], v[76:79]
	v_mfma_i32_16x16x64_i8 v[72:75], v[140:143], v[208:211], v[72:75]
	s_setprio 0
	s_setprio 1
	v_mfma_i32_16x16x64_i8 v[116:119], v[164:167], v[180:183], v[116:119]
	v_mfma_i32_16x16x64_i8 v[112:115], v[172:175], v[180:183], v[112:115]
	v_mfma_i32_16x16x64_i8 v[100:103], v[164:167], v[188:191], v[100:103]
	v_mfma_i32_16x16x64_i8 v[96:99], v[172:175], v[188:191], v[96:99]
	v_mfma_i32_16x16x64_i8 v[84:87], v[164:167], v[196:199], v[84:87]
	v_mfma_i32_16x16x64_i8 v[80:83], v[172:175], v[196:199], v[80:83]
	v_mfma_i32_16x16x64_i8 v[68:71], v[164:167], v[204:207], v[68:71]
	v_mfma_i32_16x16x64_i8 v[64:67], v[172:175], v[204:207], v[64:67]
	v_mfma_i32_16x16x64_i8 v[116:119], v[168:171], v[184:187], v[116:119]
	v_mfma_i32_16x16x64_i8 v[112:115], v[176:179], v[184:187], v[112:115]
	v_mfma_i32_16x16x64_i8 v[100:103], v[168:171], v[192:195], v[100:103]
	v_mfma_i32_16x16x64_i8 v[96:99], v[176:179], v[192:195], v[96:99]
	v_mfma_i32_16x16x64_i8 v[84:87], v[168:171], v[200:203], v[84:87]
	v_mfma_i32_16x16x64_i8 v[80:83], v[176:179], v[200:203], v[80:83]
	v_mfma_i32_16x16x64_i8 v[68:71], v[168:171], v[208:211], v[68:71]
	v_mfma_i32_16x16x64_i8 v[64:67], v[176:179], v[208:211], v[64:67]
	s_setprio 0
	s_barrier
; #define PG8_STAGE(bufoff, gbase, voff) do { _Pragma("unroll") for (int _i = 0; _i < 2; ++_i) \
;         __builtin_amdgcn_global_load_lds((const unsigned*)((const char*)(gbase) + (voff)[_i]), (LAS unsigned*)(lds + (bufoff) + ldsw + _i * 8192), 16, 0, 0); } while (0)
; #define PG8_LDA(dst, b, h) do { _Pragma("unroll") for (int m = 0; m < 4; ++m) _Pragma("unroll") for (int k = 0; k < 2; ++k) dst[m][k] = *(const LAS bf16x8*)(lds + PG8_SA(b, h) + aoff + m * 2048 + k * 1024); } while (0)
; #define PG8_WAIT_V(n) asm volatile("s_waitcnt vmcnt(" #n ")" ::: "memory")
; #define PG8_WAIT_L(n) asm volatile("s_waitcnt lgkmcnt(" #n ")" ::: "memory")
; #define PG8_BAR __builtin_amdgcn_s_barrier()
; #define PG8_SCHED __builtin_amdgcn_sched_barrier(0)
; template <class Epi, class Sched, bool ALIGN_EPI, bool I8 = false>
; __device__ __forceinline__ void gemm_phase(LAS unsigned char* lds, const Gemm g, const Sched& S, const Epi& E) {
;     ...
;             PG8_LDA(At, 1, 1); PG8_STAGE(PG8_SB(1, 0), b3, voffB); PG8_STAGE(PG8_SB(1, 1), b3 + hstep, voffB); PG8_STAGE(PG8_SA(1, 0), a3, voffA);
;             PG8_WAIT_V(8); PG8_WAIT_L(0); PG8_BAR; PG8_MMA(1, 0, At, B0); PG8_MMA(1, 1, At, B1); PG8_BAR; PG8_SCHED;
;         }
	s_add_i32 s4, s7, s64
	v_lshl_add_u64 v[212:213], v[212:213], 0, s[18:19]
	s_mov_b32 m0, s4
	ds_read_b128 v[180:183], v227 offset:49152
	ds_read_b128 v[184:187], v227 offset:50176
	ds_read_b128 v[188:191], v227 offset:51200
	ds_read_b128 v[192:195], v227 offset:52224
	ds_read_b128 v[196:199], v227 offset:53248
	ds_read_b128 v[200:203], v227 offset:54272
	ds_read_b128 v[204:207], v227 offset:55296
	ds_read_b128 v[208:211], v227 offset:56320
	global_load_lds_dwordx4 v[212:213], off
	s_add_i32 m0, s4, 0x2000
	s_add_u32 s4, s56, 0x40080
	v_lshl_add_u64 v[212:213], v[214:215], 0, s[18:19]
	s_addc_u32 s5, s57, 0
	s_add_i32 s7, vcc_hi, s64
	global_load_lds_dwordx4 v[212:213], off
	v_lshl_add_u64 v[212:213], s[4:5], 0, v[148:149]
	s_mov_b32 m0, s7
	s_nop 0
	global_load_lds_dwordx4 v[212:213], off
	v_lshl_add_u64 v[212:213], s[4:5], 0, v[144:145]
	s_add_i32 m0, s7, 0x2000
	s_nop 0
	global_load_lds_dwordx4 v[212:213], off
	v_lshl_add_u64 v[212:213], v[220:221], 0, s[18:19]
	s_mov_b32 m0, s73
	s_nop 0
	global_load_lds_dwordx4 v[212:213], off
	v_lshl_add_u64 v[212:213], v[228:229], 0, s[18:19]
	s_mov_b32 m0, s74
	s_nop 0
	global_load_lds_dwordx4 v[212:213], off
	s_waitcnt vmcnt(8)
	s_waitcnt lgkmcnt(0)
	s_barrier
	s_setprio 1
	s_waitcnt lgkmcnt(0)
	v_mfma_i32_16x16x64_i8 v[60:63], v[128:131], v[180:183], v[60:63]
	v_mfma_i32_16x16x64_i8 v[56:59], v[136:139], v[180:183], v[56:59]
	v_mfma_i32_16x16x64_i8 v[44:47], v[128:131], v[188:191], v[44:47]
	v_mfma_i32_16x16x64_i8 v[40:43], v[136:139], v[188:191], v[40:43]
	v_mfma_i32_16x16x64_i8 v[28:31], v[128:131], v[196:199], v[28:31]
	v_mfma_i32_16x16x64_i8 v[24:27], v[136:139], v[196:199], v[24:27]
	v_mfma_i32_16x16x64_i8 v[12:15], v[128:131], v[204:207], v[12:15]
	v_mfma_i32_16x16x64_i8 v[8:11], v[136:139], v[204:207], v[8:11]
	v_mfma_i32_16x16x64_i8 v[60:63], v[132:135], v[184:187], v[60:63]
	v_mfma_i32_16x16x64_i8 v[56:59], v[140:143], v[184:187], v[56:59]
	v_mfma_i32_16x16x64_i8 v[44:47], v[132:135], v[192:195], v[44:47]
	v_mfma_i32_16x16x64_i8 v[40:43], v[140:143], v[192:195], v[40:43]
	v_mfma_i32_16x16x64_i8 v[28:31], v[132:135], v[200:203], v[28:31]
	v_mfma_i32_16x16x64_i8 v[24:27], v[140:143], v[200:203], v[24:27]
	v_mfma_i32_16x16x64_i8 v[12:15], v[132:135], v[208:211], v[12:15]
	v_mfma_i32_16x16x64_i8 v[8:11], v[140:143], v[208:211], v[8:11]
	s_setprio 0
	s_setprio 1
	v_mfma_i32_16x16x64_i8 v[52:55], v[164:167], v[180:183], v[52:55]
	v_mfma_i32_16x16x64_i8 v[48:51], v[172:175], v[180:183], v[48:51]
	v_mfma_i32_16x16x64_i8 v[36:39], v[164:167], v[188:191], v[36:39]
	v_mfma_i32_16x16x64_i8 v[32:35], v[172:175], v[188:191], v[32:35]
	v_mfma_i32_16x16x64_i8 v[20:23], v[164:167], v[196:199], v[20:23]
	v_mfma_i32_16x16x64_i8 v[16:19], v[172:175], v[196:199], v[16:19]
	v_mfma_i32_16x16x64_i8 v[4:7], v[164:167], v[204:207], v[4:7]
	v_mfma_i32_16x16x64_i8 v[0:3], v[172:175], v[204:207], v[0:3]
	v_mfma_i32_16x16x64_i8 v[52:55], v[168:171], v[184:187], v[52:55]
	v_mfma_i32_16x16x64_i8 v[48:51], v[176:179], v[184:187], v[48:51]
	v_mfma_i32_16x16x64_i8 v[36:39], v[168:171], v[192:195], v[36:39]
	v_mfma_i32_16x16x64_i8 v[32:35], v[176:179], v[192:195], v[32:35]
	v_mfma_i32_16x16x64_i8 v[20:23], v[168:171], v[200:203], v[20:23]
	v_mfma_i32_16x16x64_i8 v[16:19], v[176:179], v[200:203], v[16:19]
	v_mfma_i32_16x16x64_i8 v[4:7], v[168:171], v[208:211], v[4:7]
	v_mfma_i32_16x16x64_i8 v[0:3], v[176:179], v[208:211], v[0:3]
	s_setprio 0
	s_barrier
	s_add_i32 vcc_lo, vcc_lo, 2
	s_add_u32 s52, s52, 0x100
	s_addc_u32 s53, s53, 0
	s_add_u32 s62, s62, 0x100
	s_addc_u32 s63, s63, 0
	s_cmp_gt_u32 vcc_lo, 13
	s_cbranch_scc1 .Lpeel_exit_22758

; #define LAS __attribute__((address_space(3)))
; __device__ __forceinline__ unsigned pk2(float lo, float hi) { f32x2 v = {lo, hi}; bf16x2_t b = __builtin_convertvector(v, bf16x2_t); return __builtin_bit_cast(unsigned, b); }
; #define MFMA32(a, b, c) __builtin_amdgcn_mfma_f32_32x32x16_bf16((a), (b), (c), 0, 0, 0)
; #define ATT_BAR() asm volatile("s_waitcnt lgkmcnt(0)\n\ts_barrier" ::: "memory")
; __device__ __forceinline__ void attn_item(const bf16_t* __restrict__ Q, const bf16_t* __restrict__ Kb, const bf16_t* __restrict__ VT, const bf16_t* __restrict__ GA, ...
;     ...
;         float ls = 0.f;
; #pragma unroll
;         for (int i = 0; i < 16; ++i) { s0[i] = __builtin_amdgcn_exp2f(s0[i]); s1[i] = __builtin_amdgcn_exp2f(s1[i]); ls += s0[i] + s1[i]; }
;         lrun += ls;
; #pragma unroll
;         for (int s = 0; s < 2; ++s) {
;             u32x4 pa, pb;
;             pa.x = pk2(s0[8 * s + 0], s0[8 * s + 1]); pa.y = pk2(s0[8 * s + 2], s0[8 * s + 3]); pa.z = pk2(s0[8 * s + 4], s0[8 * s + 5]); pa.w = pk2(s0[8 * s + 6], s0[8 * s + 7]);
;             pb.x = pk2(s1[8 * s + 0], s1[8 * s + 1]); pb.y = pk2(s1[8 * s + 2], s1[8 * s + 3]); pb.z = pk2(s1[8 * s + 4], s1[8 * s + 5]); pb.w = pk2(s1[8 * s + 6], s1[8 * s + 7]);
;             const bf16x8 va0 = *(const LAS bf16x8*)(vfp + 32 * s), va1 = *(const LAS bf16x8*)(vfp + 32 * ATP + 32 * s);
;             const bf16x8 vb0 = *(const LAS bf16x8*)(vfp + 64 + 32 * s), vb1 = *(const LAS bf16x8*)(vfp + 32 * ATP + 64 + 32 * s);
;             o0 = MFMA32(va0, __builtin_bit_cast(bf16x8, pa), o0); o1 = MFMA32(va1, __builtin_bit_cast(bf16x8, pa), o1);
;             o0 = MFMA32(vb0, __builtin_bit_cast(bf16x8, pb), o0); o1 = MFMA32(vb1, __builtin_bit_cast(bf16x8, pb), o1);
;         }
;         buf ^= 1;
; #pragma unroll
;         for (int i = 0; i < 8; ++i) *(LAS u32x4*)(pl + buf * ATT_WAVE_LDS + stoff + 8 * i * ATP) = tr[i];
;         tg += (j + 2 <= 8) ? tstep : (size_t)0;
; #pragma unroll
;         for (int i = 0; i < 8; ++i) tr[i] = *(const u32x4*)(tg + i * rstep);
;         ATT_BAR();
.LBB0_685:
	v_add3_u32 v190, s28, v165, v167
	s_xor_b32 s72, s72, 1
	s_mul_i32 s99, s72, 0x4800
	v_add_u32_e32 v226, s99, v186
	v_exp_f32_e32 v189, v50
	v_exp_f32_e32 v220, v51
	v_exp_f32_e32 v222, v52
	v_exp_f32_e32 v224, v53
	ds_read_b128 v[50:53], v190 offset:9216
	s_waitcnt vmcnt(1)
	ds_write_b128 v226, v[126:129]
	ds_write_b128 v226, v[122:125] offset:1152
	ds_write_b128 v226, v[106:109] offset:2304
	ds_write_b128 v226, v[118:121] offset:3456
	ds_write_b128 v226, v[102:105] offset:4608
	ds_write_b128 v226, v[114:117] offset:5760
	ds_write_b128 v226, v[98:101] offset:6912
	s_waitcnt vmcnt(0)
	ds_write_b128 v226, v[110:113] offset:8064
	v_exp_f32_e32 v195, v54
	v_exp_f32_e32 v194, v55
	v_exp_f32_e32 v199, v56
	v_exp_f32_e32 v198, v57
	v_exp_f32_e32 v203, v58
	v_exp_f32_e32 v202, v59
	v_pk_mov_b32 v[56:57], v[194:195], v[194:195] op_sel:[1,0]
	v_pk_mov_b32 v[58:59], v[198:199], v[198:199] op_sel:[1,0]
	v_cvt_pk_bf16_f32 v54, v189, v220
	v_cvt_pk_bf16_f32 v55, v222, v224
	v_cvt_pk_bf16_f32 v56, v56, v57
	v_cvt_pk_bf16_f32 v57, v58, v59
	v_exp_f32_e32 v197, v70
	v_exp_f32_e32 v196, v71
	s_waitcnt lgkmcnt(8)
	v_mfma_f32_32x32x16_bf16 v[2:17], v[50:53], v[54:57], v[2:17]
	v_exp_f32_e32 v201, v72
	v_exp_f32_e32 v200, v73
	v_exp_f32_e32 v216, v66
	v_exp_f32_e32 v221, v67
	v_exp_f32_e32 v223, v68
	v_exp_f32_e32 v225, v69
	v_exp_f32_e32 v207, v60
	v_exp_f32_e32 v206, v61
	v_exp_f32_e32 v211, v62
	v_exp_f32_e32 v210, v63
	v_exp_f32_e32 v215, v64
	v_exp_f32_e32 v214, v65
	ds_read_b128 v[58:61], v190 offset:9280
	ds_read_b128 v[62:65], v190 offset:9248
	v_pk_mov_b32 v[52:53], v[196:197], v[196:197] op_sel:[1,0]
	v_pk_mov_b32 v[66:67], v[200:201], v[200:201] op_sel:[1,0]
	v_cvt_pk_bf16_f32 v50, v216, v221
	v_cvt_pk_bf16_f32 v51, v223, v225
	v_cvt_pk_bf16_f32 v52, v52, v53
	v_cvt_pk_bf16_f32 v53, v66, v67
	v_pk_mov_b32 v[70:71], v[214:215], v[214:215] op_sel:[1,0]
	ds_read_b128 v[66:69], v190 offset:9312
	s_waitcnt lgkmcnt(2)
	v_mfma_f32_32x32x16_bf16 v[2:17], v[58:61], v[50:53], v[2:17]
	v_pk_mov_b32 v[58:59], v[202:203], v[202:203] op_sel:[1,0]
	v_pk_mov_b32 v[60:61], v[206:207], v[206:207] op_sel:[1,0]
	v_cvt_pk_bf16_f32 v58, v58, v59
	v_cvt_pk_bf16_f32 v59, v60, v61
	v_pk_mov_b32 v[60:61], v[210:211], v[210:211] op_sel:[1,0]
	v_exp_f32_e32 v205, v74
	v_cvt_pk_bf16_f32 v60, v60, v61
	v_cvt_pk_bf16_f32 v61, v70, v71
	v_exp_f32_e32 v204, v75
	v_exp_f32_e32 v209, v76
	s_waitcnt lgkmcnt(1)
	v_mfma_f32_32x32x16_bf16 v[2:17], v[62:65], v[58:61], v[2:17]
	v_exp_f32_e32 v208, v77
	v_exp_f32_e32 v213, v78
	v_exp_f32_e32 v212, v79
	v_exp_f32_e32 v219, v80
	v_exp_f32_e32 v218, v81
	v_pk_mov_b32 v[70:71], v[204:205], v[204:205] op_sel:[1,0]
	v_pk_mov_b32 v[72:73], v[208:209], v[208:209] op_sel:[1,0]
	s_add_i32 s70, s84, 1
	v_cvt_pk_bf16_f32 v70, v70, v71
	v_cvt_pk_bf16_f32 v71, v72, v73
	v_pk_mov_b32 v[72:73], v[212:213], v[212:213] op_sel:[1,0]
	v_pk_mov_b32 v[62:63], v[218:219], v[218:219] op_sel:[1,0]
	v_cvt_pk_bf16_f32 v72, v72, v73
	v_cvt_pk_bf16_f32 v73, v62, v63
	s_cmp_lt_i32 s84, 6
	s_waitcnt lgkmcnt(0)
	v_mfma_f32_32x32x16_bf16 v[2:17], v[66:69], v[70:73], v[2:17]
	s_cselect_b32 s7, s64, 0
	s_lshl_b32 s28, s7, 1
	v_lshl_add_u64 v[152:153], v[152:153], 0, s[28:29]
	s_mov_b32 s67, s29
	ds_read_b128 v[62:65], v190 offset:13824
	ds_read_b128 v[74:77], v190 offset:13856
	ds_read_b128 v[78:81], v190 offset:13888
	ds_read_b128 v[190:193], v190 offset:13920
	v_lshl_add_u64 v[66:67], v[152:153], 0, s[66:67]
	v_lshl_add_u64 v[68:69], v[66:67], 0, s[68:69]
	global_load_dwordx4 v[122:125], v[66:67], off
	global_load_dwordx4 v[106:109], v[68:69], off
	v_lshl_add_u64 v[66:67], v[68:69], 0, s[68:69]
	v_lshl_add_u64 v[68:69], v[66:67], 0, s[68:69]
	global_load_dwordx4 v[118:121], v[66:67], off
	global_load_dwordx4 v[102:105], v[68:69], off
	v_lshl_add_u64 v[66:67], v[68:69], 0, s[68:69]
	v_lshl_add_u64 v[68:69], v[66:67], 0, s[68:69]
	global_load_dwordx4 v[114:117], v[66:67], off
	global_load_dwordx4 v[98:101], v[68:69], off
	v_lshl_add_u64 v[66:67], v[68:69], 0, s[68:69]
	global_load_dwordx4 v[126:129], v[152:153], off
	global_load_dwordx4 v[110:113], v[66:67], off
	s_waitcnt lgkmcnt(3)
	v_mfma_f32_32x32x16_bf16 v[18:33], v[62:65], v[54:57], v[18:33]
	v_add_f32_e32 v189, v216, v189
	v_add_f32_e32 v216, v221, v220
	v_add_f32_e32 v189, 0, v189
	v_add_f32_e32 v220, v223, v222
	v_add_f32_e32 v189, v216, v189
	v_add_f32_e32 v221, v225, v224
	v_pk_add_f32 v[66:67], v[196:197], v[194:195]
	s_waitcnt lgkmcnt(1)
	v_mfma_f32_32x32x16_bf16 v[18:33], v[78:81], v[50:53], v[18:33]
	v_add_f32_e32 v50, v220, v189
	v_add_f32_e32 v50, v221, v50
	v_add_f32_e32 v50, v67, v50
	v_add_f32_e64 v54, v200, v198
	v_add_f32_e64 v55, v201, v199
	v_add_f32_e32 v50, v66, v50
	v_add_f32_e32 v50, v55, v50
	v_pk_add_f32 v[56:57], v[204:205], v[202:203]
	v_mfma_f32_32x32x16_bf16 v[18:33], v[74:77], v[58:61], v[18:33]
	v_add_f32_e32 v50, v54, v50
	v_add_f32_e32 v50, v57, v50
	v_add_f32_e64 v62, v208, v206
	v_add_f32_e64 v63, v209, v207
	v_add_f32_e32 v50, v56, v50
	v_add_f32_e32 v50, v63, v50
	v_pk_add_f32 v[64:65], v[212:213], v[210:211]
	v_add_f32_e32 v50, v62, v50
	s_waitcnt lgkmcnt(0)
	v_mfma_f32_32x32x16_bf16 v[18:33], v[190:193], v[70:73], v[18:33]
	v_add_f32_e32 v50, v65, v50
	v_add_f32_e64 v68, v218, v214
	v_add_f32_e64 v69, v219, v215
	v_add_f32_e32 v50, v64, v50
	v_add_f32_e32 v50, v69, v50
	s_waitcnt lgkmcnt(0)
	s_barrier
	v_add_f32_e32 v50, v68, v50
	v_add_f32_e32 v187, v187, v50
	s_cmp_lt_i32 s84, 7
	v_add_u32_e32 v188, 0xffffff00, v188
	s_cbranch_scc0 .LBB0_641
	s_mov_b32 s84, s70
	s_branch .LBB0_679

; __global__ void __launch_bounds__(512, 2) mk_fwd(const Args args) {
	.amdhsa_kernel _Z6mk_fwd4Args
		.amdhsa_group_segment_fixed_size 0
		.amdhsa_private_segment_fixed_size 0
		.amdhsa_kernarg_size 392
		.amdhsa_user_sgpr_count 2
		.amdhsa_user_sgpr_dispatch_ptr 0
		.amdhsa_user_sgpr_queue_ptr 0
		.amdhsa_user_sgpr_kernarg_segment_ptr 1
		.amdhsa_user_sgpr_dispatch_id 0
		.amdhsa_user_sgpr_kernarg_preload_length 0
		.amdhsa_user_sgpr_kernarg_preload_offset 0
		.amdhsa_user_sgpr_private_segment_size 0
		.amdhsa_uses_dynamic_stack 0
		.amdhsa_enable_private_segment 0
		.amdhsa_system_sgpr_workgroup_id_x 1
		.amdhsa_system_sgpr_workgroup_id_y 0
		.amdhsa_system_sgpr_workgroup_id_z 0
		.amdhsa_system_sgpr_workgroup_info 0
		.amdhsa_system_vgpr_workitem_id 2
		.amdhsa_next_free_vgpr 245
		.amdhsa_next_free_sgpr 100
		.amdhsa_accum_offset 248
		.amdhsa_reserve_vcc 1
		.amdhsa_float_round_mode_32 0
		.amdhsa_float_round_mode_16_64 0
		.amdhsa_float_denorm_mode_32 3
		.amdhsa_float_denorm_mode_16_64 3
		.amdhsa_dx10_clamp 1
		.amdhsa_ieee_mode 1
		.amdhsa_fp16_overflow 0
		.amdhsa_tg_split 0
		.amdhsa_exception_fp_ieee_invalid_op 0
		.amdhsa_exception_fp_denorm_src 0
		.amdhsa_exception_fp_ieee_div_zero 0
		.amdhsa_exception_fp_ieee_overflow 0
		.amdhsa_exception_fp_ieee_underflow 0
		.amdhsa_exception_fp_ieee_inexact 0
		.amdhsa_exception_int_div_zero 0
	.end_amdhsa_kernel

; __global__ void __launch_bounds__(512, 2) mk_fwd(const Args args) {
amdhsa.kernels:
  - .agpr_count:     0
    .args:
      - .offset:         0
        .size:           136
        .value_kind:     by_value
      - .offset:         136
        .size:           4
        .value_kind:     hidden_block_count_x
      - .offset:         140
        .size:           4
        .value_kind:     hidden_block_count_y
      - .offset:         144
        .size:           4
        .value_kind:     hidden_block_count_z
      - .offset:         148
        .size:           2
        .value_kind:     hidden_group_size_x
      - .offset:         150
        .size:           2
        .value_kind:     hidden_group_size_y
      - .offset:         152
        .size:           2
        .value_kind:     hidden_group_size_z
      - .offset:         154
        .size:           2
        .value_kind:     hidden_remainder_x
      - .offset:         156
        .size:           2
        .value_kind:     hidden_remainder_y
      - .offset:         158
        .size:           2
        .value_kind:     hidden_remainder_z
      - .offset:         176
        .size:           8
        .value_kind:     hidden_global_offset_x
      - .offset:         184
        .size:           8
        .value_kind:     hidden_global_offset_y
      - .offset:         192
        .size:           8
        .value_kind:     hidden_global_offset_z
      - .offset:         200
        .size:           2
        .value_kind:     hidden_grid_dims
      - .offset:         224
        .size:           8
        .value_kind:     hidden_multigrid_sync_arg
      - .offset:         256
        .size:           4
        .value_kind:     hidden_dynamic_lds_size
    .group_segment_fixed_size: 0
    .kernarg_segment_align: 8
    .kernarg_segment_size: 392
    .language:       OpenCL C
    .language_version:
      - 2
      - 0
    .max_flat_workgroup_size: 512
    .name:           _Z6mk_fwd4Args
    .private_segment_fixed_size: 0
    .sgpr_count:     106
    .sgpr_spill_count: 12
    .symbol:         _Z6mk_fwd4Args.kd
    .uniform_work_group_size: 1
    .uses_dynamic_stack: false
    .vgpr_count:     245
    .vgpr_spill_count: 0
    .wavefront_size: 64
